# v17: v7 + per-unit overlap of accumulator zeroing with the first load segment (first segment's ds_reads and LDS-DMA issued before the 128 acc v_movs, loop entered at its waits)
# baseline (speedup 1.0000x reference)
.LBB0_188:
	s_ashr_i32 s21, s20, 31
	s_lshl_b64 s[22:23], s[20:21], 20
	s_add_u32 s22, s37, s22
	s_addc_u32 s23, s38, s23
	s_and_b64 s[24:25], s[4:5], exec
	s_cselect_b32 s21, s23, s29
	s_cselect_b32 s42, s22, s28
	s_ashr_i32 s19, s18, 31
	s_lshl_b64 s[24:25], s[18:19], 20
	s_add_u32 s24, s39, s24
	s_addc_u32 s25, s40, s25
	s_and_b64 s[34:35], s[4:5], exec
	s_cselect_b32 s19, s25, s31
	s_cselect_b32 s43, s24, s30
	s_add_u32 s28, s28, 0x80080
	s_addc_u32 s29, s29, 0
	s_add_u32 s62, s30, 0x100
	s_addc_u32 s63, s31, 0
	s_mov_b32 s66, -2
	s_waitcnt vmcnt(0)
	s_add_u32 s30, s28, 0xfff80080
	s_addc_u32 s31, s29, -1
	s_add_i32 s67, 0, 0x10000
	s_cmp_eq_u32 s66, 28
	s_cselect_b32 s35, s21, s31
	s_cselect_b32 s34, s42, s30
	s_cselect_b32 s31, s19, s63
	s_cselect_b32 s30, s43, s62
	s_add_i32 s70, 0, 0x14000
	v_add_u32_e32 v84, s67, v181
	v_add_u32_e32 v156, s70, v181
	ds_read_b128 v[64:67], v84
	ds_read_b128 v[72:75], v84 offset:1024
	ds_read_b128 v[80:83], v84 offset:2048
	ds_read_b128 v[84:87], v84 offset:3072
	ds_read_b128 v[144:147], v156
	ds_read_b128 v[148:151], v156 offset:1024
	ds_read_b128 v[152:155], v156 offset:2048
	ds_read_b128 v[156:159], v156 offset:3072
	v_lshl_add_u64 v[212:213], s[28:29], 0, v[168:169]
	s_add_i32 m0, s27, 0xc000
	ds_read_b128 v[172:175], v182
	ds_read_b128 v[176:179], v182 offset:1024
	ds_read_b128 v[184:187], v182 offset:2048
	ds_read_b128 v[188:191], v182 offset:3072
	ds_read_b128 v[192:195], v182 offset:4096
	ds_read_b128 v[196:199], v182 offset:5120
	ds_read_b128 v[202:205], v182 offset:6144
	ds_read_b128 v[206:209], v182 offset:7168
	global_load_lds_dwordx4 v[212:213], off
	v_lshl_add_u64 v[212:213], s[28:29], 0, v[170:171]
	s_add_i32 m0, s27, 0xe000
	s_nop 0
	global_load_lds_dwordx4 v[212:213], off
	v_mov_b32_e32 v0, v180
	v_mov_b32_e32 v1, v180
	v_mov_b32_e32 v2, v180
	v_mov_b32_e32 v3, v180
	v_mov_b32_e32 v4, v180
	v_mov_b32_e32 v5, v180
	v_mov_b32_e32 v6, v180
	v_mov_b32_e32 v7, v180
	v_mov_b32_e32 v16, v180
	v_mov_b32_e32 v17, v180
	v_mov_b32_e32 v18, v180
	v_mov_b32_e32 v19, v180
	v_mov_b32_e32 v20, v180
	v_mov_b32_e32 v21, v180
	v_mov_b32_e32 v22, v180
	v_mov_b32_e32 v23, v180
	v_mov_b32_e32 v32, v180
	v_mov_b32_e32 v33, v180
	v_mov_b32_e32 v34, v180
	v_mov_b32_e32 v35, v180
	v_mov_b32_e32 v36, v180
	v_mov_b32_e32 v37, v180
	v_mov_b32_e32 v38, v180
	v_mov_b32_e32 v39, v180
	v_mov_b32_e32 v48, v180
	v_mov_b32_e32 v49, v180
	v_mov_b32_e32 v50, v180
	v_mov_b32_e32 v51, v180
	v_mov_b32_e32 v52, v180
	v_mov_b32_e32 v53, v180
	v_mov_b32_e32 v54, v180
	v_mov_b32_e32 v55, v180
	v_mov_b32_e32 v8, v180
	v_mov_b32_e32 v9, v180
	v_mov_b32_e32 v10, v180
	v_mov_b32_e32 v11, v180
	v_mov_b32_e32 v12, v180
	v_mov_b32_e32 v13, v180
	v_mov_b32_e32 v14, v180
	v_mov_b32_e32 v15, v180
	v_mov_b32_e32 v24, v180
	v_mov_b32_e32 v25, v180
	v_mov_b32_e32 v26, v180
	v_mov_b32_e32 v27, v180
	v_mov_b32_e32 v28, v180
	v_mov_b32_e32 v29, v180
	v_mov_b32_e32 v30, v180
	v_mov_b32_e32 v31, v180
	v_mov_b32_e32 v40, v180
	v_mov_b32_e32 v41, v180
	v_mov_b32_e32 v42, v180
	v_mov_b32_e32 v43, v180
	v_mov_b32_e32 v44, v180
	v_mov_b32_e32 v45, v180
	v_mov_b32_e32 v46, v180
	v_mov_b32_e32 v47, v180
	v_mov_b32_e32 v56, v180
	v_mov_b32_e32 v57, v180
	v_mov_b32_e32 v58, v180
	v_mov_b32_e32 v59, v180
	v_mov_b32_e32 v60, v180
	v_mov_b32_e32 v61, v180
	v_mov_b32_e32 v62, v180
	v_mov_b32_e32 v63, v180
	v_mov_b32_e32 v68, v180
	v_mov_b32_e32 v69, v180
	v_mov_b32_e32 v70, v180
	v_mov_b32_e32 v71, v180
	v_mov_b32_e32 v76, v180
	v_mov_b32_e32 v77, v180
	v_mov_b32_e32 v78, v180
	v_mov_b32_e32 v79, v180
	v_mov_b32_e32 v96, v180
	v_mov_b32_e32 v97, v180
	v_mov_b32_e32 v98, v180
	v_mov_b32_e32 v99, v180
	v_mov_b32_e32 v100, v180
	v_mov_b32_e32 v101, v180
	v_mov_b32_e32 v102, v180
	v_mov_b32_e32 v103, v180
	v_mov_b32_e32 v112, v180
	v_mov_b32_e32 v113, v180
	v_mov_b32_e32 v114, v180
	v_mov_b32_e32 v115, v180
	v_mov_b32_e32 v116, v180
	v_mov_b32_e32 v117, v180
	v_mov_b32_e32 v118, v180
	v_mov_b32_e32 v119, v180
	v_mov_b32_e32 v128, v180
	v_mov_b32_e32 v129, v180
	v_mov_b32_e32 v130, v180
	v_mov_b32_e32 v131, v180
	v_mov_b32_e32 v132, v180
	v_mov_b32_e32 v133, v180
	v_mov_b32_e32 v134, v180
	v_mov_b32_e32 v135, v180
	v_mov_b32_e32 v88, v180
	v_mov_b32_e32 v89, v180
	v_mov_b32_e32 v90, v180
	v_mov_b32_e32 v91, v180
	v_mov_b32_e32 v92, v180
	v_mov_b32_e32 v93, v180
	v_mov_b32_e32 v94, v180
	v_mov_b32_e32 v95, v180
	v_mov_b32_e32 v104, v180
	v_mov_b32_e32 v105, v180
	v_mov_b32_e32 v106, v180
	v_mov_b32_e32 v107, v180
	v_mov_b32_e32 v108, v180
	v_mov_b32_e32 v109, v180
	v_mov_b32_e32 v110, v180
	v_mov_b32_e32 v111, v180
	v_mov_b32_e32 v120, v180
	v_mov_b32_e32 v121, v180
	v_mov_b32_e32 v122, v180
	v_mov_b32_e32 v123, v180
	v_mov_b32_e32 v124, v180
	v_mov_b32_e32 v125, v180
	v_mov_b32_e32 v126, v180
	v_mov_b32_e32 v127, v180
	v_mov_b32_e32 v136, v180
	v_mov_b32_e32 v137, v180
	v_mov_b32_e32 v138, v180
	v_mov_b32_e32 v139, v180
	v_mov_b32_e32 v140, v180
	v_mov_b32_e32 v141, v180
	v_mov_b32_e32 v142, v180
	v_mov_b32_e32 v143, v180
	s_branch .Lz189_mid

.Lz189_mid:
	s_waitcnt vmcnt(8)
	s_waitcnt lgkmcnt(0)
	s_setprio 1
	s_barrier
	v_mfma_f32_16x16x32_bf16 v[140:143], v[64:67], v[172:175], v[140:143]
	v_mfma_f32_16x16x32_bf16 v[136:139], v[80:83], v[172:175], v[136:139]
	v_mfma_f32_16x16x32_bf16 v[124:127], v[64:67], v[184:187], v[124:127]
	v_mfma_f32_16x16x32_bf16 v[120:123], v[80:83], v[184:187], v[120:123]
	v_mfma_f32_16x16x32_bf16 v[108:111], v[64:67], v[192:195], v[108:111]
	v_mfma_f32_16x16x32_bf16 v[104:107], v[80:83], v[192:195], v[104:107]
	v_mfma_f32_16x16x32_bf16 v[92:95], v[64:67], v[202:205], v[92:95]
	v_mfma_f32_16x16x32_bf16 v[88:91], v[80:83], v[202:205], v[88:91]
	v_mfma_f32_16x16x32_bf16 v[140:143], v[72:75], v[176:179], v[140:143]
	v_mfma_f32_16x16x32_bf16 v[136:139], v[84:87], v[176:179], v[136:139]
	v_mfma_f32_16x16x32_bf16 v[124:127], v[72:75], v[188:191], v[124:127]
	v_mfma_f32_16x16x32_bf16 v[120:123], v[84:87], v[188:191], v[120:123]
	v_mfma_f32_16x16x32_bf16 v[108:111], v[72:75], v[196:199], v[108:111]
	v_mfma_f32_16x16x32_bf16 v[104:107], v[84:87], v[196:199], v[104:107]
	v_mfma_f32_16x16x32_bf16 v[92:95], v[72:75], v[206:209], v[92:95]
	v_mfma_f32_16x16x32_bf16 v[88:91], v[84:87], v[206:209], v[88:91]
	s_setprio 0
	s_setprio 1
	v_mfma_f32_16x16x32_bf16 v[132:135], v[144:147], v[172:175], v[132:135]
	v_mfma_f32_16x16x32_bf16 v[128:131], v[152:155], v[172:175], v[128:131]
	v_mfma_f32_16x16x32_bf16 v[116:119], v[144:147], v[184:187], v[116:119]
	v_mfma_f32_16x16x32_bf16 v[112:115], v[152:155], v[184:187], v[112:115]
	v_mfma_f32_16x16x32_bf16 v[100:103], v[144:147], v[192:195], v[100:103]
	v_mfma_f32_16x16x32_bf16 v[96:99], v[152:155], v[192:195], v[96:99]
	v_mfma_f32_16x16x32_bf16 v[76:79], v[144:147], v[202:205], v[76:79]
	v_mfma_f32_16x16x32_bf16 v[68:71], v[152:155], v[202:205], v[68:71]
	v_mfma_f32_16x16x32_bf16 v[132:135], v[148:151], v[176:179], v[132:135]
	v_mfma_f32_16x16x32_bf16 v[128:131], v[156:159], v[176:179], v[128:131]
	v_mfma_f32_16x16x32_bf16 v[116:119], v[148:151], v[188:191], v[116:119]
	v_mfma_f32_16x16x32_bf16 v[112:115], v[156:159], v[188:191], v[112:115]
	v_mfma_f32_16x16x32_bf16 v[100:103], v[148:151], v[196:199], v[100:103]
	v_mfma_f32_16x16x32_bf16 v[96:99], v[156:159], v[196:199], v[96:99]
	v_mfma_f32_16x16x32_bf16 v[76:79], v[148:151], v[206:209], v[76:79]
	v_mfma_f32_16x16x32_bf16 v[68:71], v[156:159], v[206:209], v[68:71]
	s_barrier
	s_setprio 0
	s_add_i32 s67, s67, s41
	v_lshl_add_u64 v[212:213], s[30:31], 0, v[162:163]
	s_mov_b32 m0, s67
	ds_read_b128 v[172:175], v182 offset:16384
	ds_read_b128 v[176:179], v182 offset:17408
	ds_read_b128 v[184:187], v182 offset:18432
	ds_read_b128 v[188:191], v182 offset:19456
	ds_read_b128 v[192:195], v182 offset:20480
	ds_read_b128 v[196:199], v182 offset:21504
	ds_read_b128 v[202:205], v182 offset:22528
	ds_read_b128 v[206:209], v182 offset:23552
	global_load_lds_dwordx4 v[212:213], off
	s_add_i32 m0, s67, 0x2000
	s_add_u32 s68, s30, 0x80000
	v_lshl_add_u64 v[214:215], s[30:31], 0, v[166:167]
	s_addc_u32 s69, s31, 0
	s_add_i32 s67, s70, s41
	global_load_lds_dwordx4 v[214:215], off
	v_lshl_add_u64 v[216:217], s[68:69], 0, v[162:163]
	s_mov_b32 m0, s67
	v_lshl_add_u64 v[218:219], s[34:35], 0, v[164:165]
	global_load_lds_dwordx4 v[216:217], off
	v_lshl_add_u64 v[216:217], s[68:69], 0, v[166:167]
	s_add_i32 m0, s67, 0x2000
	s_nop 0
	global_load_lds_dwordx4 v[216:217], off
	v_lshl_add_u64 v[216:217], s[34:35], 0, v[160:161]
	s_mov_b32 m0, s27
	s_nop 0
	global_load_lds_dwordx4 v[216:217], off
	s_mov_b32 m0, s48
	s_nop 0
	global_load_lds_dwordx4 v[218:219], off
	s_waitcnt vmcnt(8)
	s_waitcnt lgkmcnt(0)
	s_setprio 1
	s_barrier
	v_mfma_f32_16x16x32_bf16 v[60:63], v[64:67], v[172:175], v[60:63]
	v_mfma_f32_16x16x32_bf16 v[56:59], v[80:83], v[172:175], v[56:59]
	v_mfma_f32_16x16x32_bf16 v[44:47], v[64:67], v[184:187], v[44:47]
	v_mfma_f32_16x16x32_bf16 v[40:43], v[80:83], v[184:187], v[40:43]
	v_mfma_f32_16x16x32_bf16 v[28:31], v[64:67], v[192:195], v[28:31]
	v_mfma_f32_16x16x32_bf16 v[24:27], v[80:83], v[192:195], v[24:27]
	v_mfma_f32_16x16x32_bf16 v[12:15], v[64:67], v[202:205], v[12:15]
	v_mfma_f32_16x16x32_bf16 v[8:11], v[80:83], v[202:205], v[8:11]
	v_mfma_f32_16x16x32_bf16 v[60:63], v[72:75], v[176:179], v[60:63]
	v_mfma_f32_16x16x32_bf16 v[56:59], v[84:87], v[176:179], v[56:59]
	v_mfma_f32_16x16x32_bf16 v[44:47], v[72:75], v[188:191], v[44:47]
	v_mfma_f32_16x16x32_bf16 v[40:43], v[84:87], v[188:191], v[40:43]
	v_mfma_f32_16x16x32_bf16 v[28:31], v[72:75], v[196:199], v[28:31]
	v_mfma_f32_16x16x32_bf16 v[24:27], v[84:87], v[196:199], v[24:27]
	v_mfma_f32_16x16x32_bf16 v[12:15], v[72:75], v[206:209], v[12:15]
	v_mfma_f32_16x16x32_bf16 v[8:11], v[84:87], v[206:209], v[8:11]
	s_setprio 0
	s_setprio 1
	v_mfma_f32_16x16x32_bf16 v[52:55], v[144:147], v[172:175], v[52:55]
	v_mfma_f32_16x16x32_bf16 v[48:51], v[152:155], v[172:175], v[48:51]
	v_mfma_f32_16x16x32_bf16 v[36:39], v[144:147], v[184:187], v[36:39]
	v_mfma_f32_16x16x32_bf16 v[32:35], v[152:155], v[184:187], v[32:35]
	v_mfma_f32_16x16x32_bf16 v[20:23], v[144:147], v[192:195], v[20:23]
	v_mfma_f32_16x16x32_bf16 v[16:19], v[152:155], v[192:195], v[16:19]
	v_mfma_f32_16x16x32_bf16 v[4:7], v[144:147], v[202:205], v[4:7]
	v_mfma_f32_16x16x32_bf16 v[0:3], v[152:155], v[202:205], v[0:3]
	v_mfma_f32_16x16x32_bf16 v[52:55], v[148:151], v[176:179], v[52:55]
	v_mfma_f32_16x16x32_bf16 v[48:51], v[156:159], v[176:179], v[48:51]
	v_mfma_f32_16x16x32_bf16 v[36:39], v[148:151], v[188:191], v[36:39]
	v_mfma_f32_16x16x32_bf16 v[32:35], v[156:159], v[188:191], v[32:35]
	v_mfma_f32_16x16x32_bf16 v[20:23], v[148:151], v[196:199], v[20:23]
	v_mfma_f32_16x16x32_bf16 v[16:19], v[156:159], v[196:199], v[16:19]
	v_mfma_f32_16x16x32_bf16 v[4:7], v[148:151], v[206:209], v[4:7]
	v_mfma_f32_16x16x32_bf16 v[0:3], v[156:159], v[206:209], v[0:3]
	s_barrier
	s_setprio 0
	s_add_i32 s67, 0, 0x18000
	s_add_i32 s68, 0, 0x1c000
	v_add_u32_e32 v84, s67, v181
	v_add_u32_e32 v156, s68, v181
	ds_read_b128 v[64:67], v84
	ds_read_b128 v[72:75], v84 offset:1024
	ds_read_b128 v[80:83], v84 offset:2048
	ds_read_b128 v[84:87], v84 offset:3072
	ds_read_b128 v[144:147], v156
	ds_read_b128 v[148:151], v156 offset:1024
	ds_read_b128 v[152:155], v156 offset:2048
	ds_read_b128 v[156:159], v156 offset:3072
	s_add_u32 s34, s34, 0x80000
	s_addc_u32 s35, s35, 0
	s_mov_b32 m0, s49
	v_lshl_add_u64 v[220:221], s[34:35], 0, v[160:161]
	ds_read_b128 v[172:175], v182 offset:32768
	ds_read_b128 v[176:179], v182 offset:33792
	ds_read_b128 v[184:187], v182 offset:34816
	ds_read_b128 v[188:191], v182 offset:35840
	ds_read_b128 v[192:195], v182 offset:36864
	ds_read_b128 v[196:199], v182 offset:37888
	ds_read_b128 v[202:205], v182 offset:38912
	ds_read_b128 v[206:209], v182 offset:39936
	global_load_lds_dwordx4 v[220:221], off
	v_lshl_add_u64 v[220:221], s[34:35], 0, v[164:165]
	s_mov_b32 m0, s50
	s_nop 0
	global_load_lds_dwordx4 v[220:221], off
	s_waitcnt vmcnt(8)
	s_waitcnt lgkmcnt(0)
	s_setprio 1
	s_barrier
	v_mfma_f32_16x16x32_bf16 v[140:143], v[64:67], v[172:175], v[140:143]
	v_mfma_f32_16x16x32_bf16 v[136:139], v[80:83], v[172:175], v[136:139]
	v_mfma_f32_16x16x32_bf16 v[124:127], v[64:67], v[184:187], v[124:127]
	v_mfma_f32_16x16x32_bf16 v[120:123], v[80:83], v[184:187], v[120:123]
	v_mfma_f32_16x16x32_bf16 v[108:111], v[64:67], v[192:195], v[108:111]
	v_mfma_f32_16x16x32_bf16 v[104:107], v[80:83], v[192:195], v[104:107]
	v_mfma_f32_16x16x32_bf16 v[92:95], v[64:67], v[202:205], v[92:95]
	v_mfma_f32_16x16x32_bf16 v[88:91], v[80:83], v[202:205], v[88:91]
	v_mfma_f32_16x16x32_bf16 v[140:143], v[72:75], v[176:179], v[140:143]
	v_mfma_f32_16x16x32_bf16 v[136:139], v[84:87], v[176:179], v[136:139]
	v_mfma_f32_16x16x32_bf16 v[124:127], v[72:75], v[188:191], v[124:127]
	v_mfma_f32_16x16x32_bf16 v[120:123], v[84:87], v[188:191], v[120:123]
	v_mfma_f32_16x16x32_bf16 v[108:111], v[72:75], v[196:199], v[108:111]
	v_mfma_f32_16x16x32_bf16 v[104:107], v[84:87], v[196:199], v[104:107]
	v_mfma_f32_16x16x32_bf16 v[92:95], v[72:75], v[206:209], v[92:95]
	v_mfma_f32_16x16x32_bf16 v[88:91], v[84:87], v[206:209], v[88:91]
	s_setprio 0
	s_setprio 1
	v_mfma_f32_16x16x32_bf16 v[132:135], v[144:147], v[172:175], v[132:135]
	v_mfma_f32_16x16x32_bf16 v[128:131], v[152:155], v[172:175], v[128:131]
	v_mfma_f32_16x16x32_bf16 v[116:119], v[144:147], v[184:187], v[116:119]
	v_mfma_f32_16x16x32_bf16 v[112:115], v[152:155], v[184:187], v[112:115]
	v_mfma_f32_16x16x32_bf16 v[100:103], v[144:147], v[192:195], v[100:103]
	v_mfma_f32_16x16x32_bf16 v[96:99], v[152:155], v[192:195], v[96:99]
	v_mfma_f32_16x16x32_bf16 v[76:79], v[144:147], v[202:205], v[76:79]
	v_mfma_f32_16x16x32_bf16 v[68:71], v[152:155], v[202:205], v[68:71]
	v_mfma_f32_16x16x32_bf16 v[132:135], v[148:151], v[176:179], v[132:135]
	v_mfma_f32_16x16x32_bf16 v[128:131], v[156:159], v[176:179], v[128:131]
	v_mfma_f32_16x16x32_bf16 v[116:119], v[148:151], v[188:191], v[116:119]
	v_mfma_f32_16x16x32_bf16 v[112:115], v[156:159], v[188:191], v[112:115]
	v_mfma_f32_16x16x32_bf16 v[100:103], v[148:151], v[196:199], v[100:103]
	v_mfma_f32_16x16x32_bf16 v[96:99], v[156:159], v[196:199], v[96:99]
	v_mfma_f32_16x16x32_bf16 v[76:79], v[148:151], v[206:209], v[76:79]
	v_mfma_f32_16x16x32_bf16 v[68:71], v[156:159], v[206:209], v[68:71]
	s_barrier
	s_setprio 0
	s_add_i32 s34, s67, s41
	v_lshl_add_u64 v[212:213], v[212:213], 0, s[64:65]
	s_mov_b32 m0, s34
	ds_read_b128 v[172:175], v182 offset:49152
	ds_read_b128 v[176:179], v182 offset:50176
	ds_read_b128 v[184:187], v182 offset:51200
	ds_read_b128 v[188:191], v182 offset:52224
	ds_read_b128 v[192:195], v182 offset:53248
	ds_read_b128 v[196:199], v182 offset:54272
	ds_read_b128 v[202:205], v182 offset:55296
	ds_read_b128 v[206:209], v182 offset:56320
	global_load_lds_dwordx4 v[212:213], off
	s_add_i32 m0, s34, 0x2000
	s_add_u32 s30, s30, 0x80080
	v_lshl_add_u64 v[212:213], v[214:215], 0, s[64:65]
	s_addc_u32 s31, s31, 0
	s_add_i32 s34, s68, s41
	global_load_lds_dwordx4 v[212:213], off
	v_lshl_add_u64 v[212:213], s[30:31], 0, v[162:163]
	s_mov_b32 m0, s34
	s_nop 0
	global_load_lds_dwordx4 v[212:213], off
	v_lshl_add_u64 v[212:213], s[30:31], 0, v[166:167]
	s_add_i32 m0, s34, 0x2000
	s_nop 0
	global_load_lds_dwordx4 v[212:213], off
	v_lshl_add_u64 v[212:213], v[216:217], 0, s[64:65]
	s_mov_b32 m0, s53
	s_nop 0
	global_load_lds_dwordx4 v[212:213], off
	v_lshl_add_u64 v[212:213], v[218:219], 0, s[64:65]
	s_mov_b32 m0, s56
	s_nop 0
	global_load_lds_dwordx4 v[212:213], off
	s_waitcnt vmcnt(8)
	s_waitcnt lgkmcnt(0)
	s_setprio 1
	s_barrier
	v_mfma_f32_16x16x32_bf16 v[60:63], v[64:67], v[172:175], v[60:63]
	v_mfma_f32_16x16x32_bf16 v[56:59], v[80:83], v[172:175], v[56:59]
	v_mfma_f32_16x16x32_bf16 v[44:47], v[64:67], v[184:187], v[44:47]
	v_mfma_f32_16x16x32_bf16 v[40:43], v[80:83], v[184:187], v[40:43]
	v_mfma_f32_16x16x32_bf16 v[28:31], v[64:67], v[192:195], v[28:31]
	v_mfma_f32_16x16x32_bf16 v[24:27], v[80:83], v[192:195], v[24:27]
	v_mfma_f32_16x16x32_bf16 v[12:15], v[64:67], v[202:205], v[12:15]
	v_mfma_f32_16x16x32_bf16 v[8:11], v[80:83], v[202:205], v[8:11]
	v_mfma_f32_16x16x32_bf16 v[60:63], v[72:75], v[176:179], v[60:63]
	v_mfma_f32_16x16x32_bf16 v[56:59], v[84:87], v[176:179], v[56:59]
	v_mfma_f32_16x16x32_bf16 v[44:47], v[72:75], v[188:191], v[44:47]
	v_mfma_f32_16x16x32_bf16 v[40:43], v[84:87], v[188:191], v[40:43]
	v_mfma_f32_16x16x32_bf16 v[28:31], v[72:75], v[196:199], v[28:31]
	v_mfma_f32_16x16x32_bf16 v[24:27], v[84:87], v[196:199], v[24:27]
	v_mfma_f32_16x16x32_bf16 v[12:15], v[72:75], v[206:209], v[12:15]
	v_mfma_f32_16x16x32_bf16 v[8:11], v[84:87], v[206:209], v[8:11]
	s_setprio 0
	s_setprio 1
	v_mfma_f32_16x16x32_bf16 v[52:55], v[144:147], v[172:175], v[52:55]
	v_mfma_f32_16x16x32_bf16 v[48:51], v[152:155], v[172:175], v[48:51]
	v_mfma_f32_16x16x32_bf16 v[36:39], v[144:147], v[184:187], v[36:39]
	v_mfma_f32_16x16x32_bf16 v[32:35], v[152:155], v[184:187], v[32:35]
	v_mfma_f32_16x16x32_bf16 v[20:23], v[144:147], v[192:195], v[20:23]
	v_mfma_f32_16x16x32_bf16 v[16:19], v[152:155], v[192:195], v[16:19]
	v_mfma_f32_16x16x32_bf16 v[4:7], v[144:147], v[202:205], v[4:7]
	v_mfma_f32_16x16x32_bf16 v[0:3], v[152:155], v[202:205], v[0:3]
	v_mfma_f32_16x16x32_bf16 v[52:55], v[148:151], v[176:179], v[52:55]
	v_mfma_f32_16x16x32_bf16 v[48:51], v[156:159], v[176:179], v[48:51]
	v_mfma_f32_16x16x32_bf16 v[36:39], v[148:151], v[188:191], v[36:39]
	v_mfma_f32_16x16x32_bf16 v[32:35], v[156:159], v[188:191], v[32:35]
	v_mfma_f32_16x16x32_bf16 v[20:23], v[148:151], v[196:199], v[20:23]
	v_mfma_f32_16x16x32_bf16 v[16:19], v[156:159], v[196:199], v[16:19]
	v_mfma_f32_16x16x32_bf16 v[4:7], v[148:151], v[206:209], v[4:7]
	v_mfma_f32_16x16x32_bf16 v[0:3], v[156:159], v[206:209], v[0:3]
	s_barrier
	s_setprio 0
	s_add_i32 s66, s66, 2
	s_add_u32 s28, s28, 0x100
	s_addc_u32 s29, s29, 0
	s_add_u32 s62, s62, 0x100
	s_addc_u32 s63, s63, 0
	s_cmp_gt_u32 s66, 29
	s_cbranch_scc0 .LBB0_189
	s_and_b64 vcc, exec, s[16:17]
	s_cbranch_vccz .LBB0_192
	s_barrier

.LBB0_642:
	s_ashr_i32 s23, s22, 31
	s_lshl_b64 s[8:9], s[22:23], 20
	s_add_u32 s24, s29, s8
	s_addc_u32 s25, s30, s9
	s_and_b64 s[8:9], s[2:3], exec
	s_cselect_b32 s1, s25, s5
	s_cselect_b32 s23, s24, s4
	s_ashr_i32 s21, s20, 31
	s_lshl_b64 s[8:9], s[20:21], 20
	s_add_u32 s26, s31, s8
	s_addc_u32 s27, s34, s9
	s_and_b64 s[8:9], s[2:3], exec
	s_cselect_b32 s21, s27, s7
	s_cselect_b32 s33, s26, s6
	s_add_u32 s4, s4, 0x80080
	s_addc_u32 s5, s5, 0
	s_add_u32 s42, s6, 0x100
	s_addc_u32 s43, s7, 0
	s_mov_b32 s49, -2
	s_waitcnt lgkmcnt(0)
	s_add_u32 s6, s4, 0xfff80080
	s_addc_u32 s7, s5, -1
	s_add_i32 s50, 0, 0x10000
	s_cmp_eq_u32 s49, 28
	s_cselect_b32 s9, s1, s7
	s_cselect_b32 s8, s23, s6
	v_add_u32_e32 v148, s50, v151
	s_cselect_b32 s7, s21, s43
	s_cselect_b32 s6, s33, s42
	s_add_i32 s53, 0, 0x14000
	ds_read_b128 v[140:143], v148
	ds_read_b128 v[144:147], v148 offset:1024
	ds_read_b128 v[154:157], v148 offset:2048
	ds_read_b128 v[158:161], v148 offset:3072
	v_add_u32_e32 v148, s53, v151
	ds_read_b128 v[162:165], v148
	ds_read_b128 v[166:169], v148 offset:1024
	ds_read_b128 v[170:173], v148 offset:2048
	ds_read_b128 v[174:177], v148 offset:3072
	v_lshl_add_u64 v[148:149], s[4:5], 0, v[136:137]
	s_add_i32 m0, s11, 0xc000
	ds_read_b128 v[178:181], v152
	ds_read_b128 v[182:185], v152 offset:1024
	ds_read_b128 v[186:189], v152 offset:2048
	ds_read_b128 v[190:193], v152 offset:3072
	ds_read_b128 v[194:197], v152 offset:4096
	ds_read_b128 v[202:205], v152 offset:5120
	ds_read_b128 v[206:209], v152 offset:6144
	ds_read_b128 v[212:215], v152 offset:7168
	global_load_lds_dwordx4 v[148:149], off
	v_lshl_add_u64 v[148:149], s[4:5], 0, v[138:139]
	s_add_i32 m0, s11, 0xe000
	s_nop 0
	global_load_lds_dwordx4 v[148:149], off
	v_mov_b32_e32 v0, v150
	v_mov_b32_e32 v1, v150
	v_mov_b32_e32 v2, v150
	v_mov_b32_e32 v3, v150
	v_mov_b32_e32 v4, v150
	v_mov_b32_e32 v5, v150
	v_mov_b32_e32 v6, v150
	v_mov_b32_e32 v7, v150
	v_mov_b32_e32 v16, v150
	v_mov_b32_e32 v17, v150
	v_mov_b32_e32 v18, v150
	v_mov_b32_e32 v19, v150
	v_mov_b32_e32 v20, v150
	v_mov_b32_e32 v21, v150
	v_mov_b32_e32 v22, v150
	v_mov_b32_e32 v23, v150
	v_mov_b32_e32 v32, v150
	v_mov_b32_e32 v33, v150
	v_mov_b32_e32 v34, v150
	v_mov_b32_e32 v35, v150
	v_mov_b32_e32 v36, v150
	v_mov_b32_e32 v37, v150
	v_mov_b32_e32 v38, v150
	v_mov_b32_e32 v39, v150
	v_mov_b32_e32 v48, v150
	v_mov_b32_e32 v49, v150
	v_mov_b32_e32 v50, v150
	v_mov_b32_e32 v51, v150
	v_mov_b32_e32 v52, v150
	v_mov_b32_e32 v53, v150
	v_mov_b32_e32 v54, v150
	v_mov_b32_e32 v55, v150
	v_mov_b32_e32 v8, v150
	v_mov_b32_e32 v9, v150
	v_mov_b32_e32 v10, v150
	v_mov_b32_e32 v11, v150
	v_mov_b32_e32 v12, v150
	v_mov_b32_e32 v13, v150
	v_mov_b32_e32 v14, v150
	v_mov_b32_e32 v15, v150
	v_mov_b32_e32 v24, v150
	v_mov_b32_e32 v25, v150
	v_mov_b32_e32 v26, v150
	v_mov_b32_e32 v27, v150
	v_mov_b32_e32 v28, v150
	v_mov_b32_e32 v29, v150
	v_mov_b32_e32 v30, v150
	v_mov_b32_e32 v31, v150
	v_mov_b32_e32 v40, v150
	v_mov_b32_e32 v41, v150
	v_mov_b32_e32 v42, v150
	v_mov_b32_e32 v43, v150
	v_mov_b32_e32 v44, v150
	v_mov_b32_e32 v45, v150
	v_mov_b32_e32 v46, v150
	v_mov_b32_e32 v47, v150
	v_mov_b32_e32 v56, v150
	v_mov_b32_e32 v57, v150
	v_mov_b32_e32 v58, v150
	v_mov_b32_e32 v59, v150
	v_mov_b32_e32 v60, v150
	v_mov_b32_e32 v61, v150
	v_mov_b32_e32 v62, v150
	v_mov_b32_e32 v63, v150
	v_mov_b32_e32 v64, v150
	v_mov_b32_e32 v65, v150
	v_mov_b32_e32 v66, v150
	v_mov_b32_e32 v67, v150
	v_mov_b32_e32 v68, v150
	v_mov_b32_e32 v69, v150
	v_mov_b32_e32 v70, v150
	v_mov_b32_e32 v71, v150
	v_mov_b32_e32 v80, v150
	v_mov_b32_e32 v81, v150
	v_mov_b32_e32 v82, v150
	v_mov_b32_e32 v83, v150
	v_mov_b32_e32 v84, v150
	v_mov_b32_e32 v85, v150
	v_mov_b32_e32 v86, v150
	v_mov_b32_e32 v87, v150
	v_mov_b32_e32 v96, v150
	v_mov_b32_e32 v97, v150
	v_mov_b32_e32 v98, v150
	v_mov_b32_e32 v99, v150
	v_mov_b32_e32 v100, v150
	v_mov_b32_e32 v101, v150
	v_mov_b32_e32 v102, v150
	v_mov_b32_e32 v103, v150
	v_mov_b32_e32 v112, v150
	v_mov_b32_e32 v113, v150
	v_mov_b32_e32 v114, v150
	v_mov_b32_e32 v115, v150
	v_mov_b32_e32 v116, v150
	v_mov_b32_e32 v117, v150
	v_mov_b32_e32 v118, v150
	v_mov_b32_e32 v119, v150
	v_mov_b32_e32 v72, v150
	v_mov_b32_e32 v73, v150
	v_mov_b32_e32 v74, v150
	v_mov_b32_e32 v75, v150
	v_mov_b32_e32 v76, v150
	v_mov_b32_e32 v77, v150
	v_mov_b32_e32 v78, v150
	v_mov_b32_e32 v79, v150
	v_mov_b32_e32 v88, v150
	v_mov_b32_e32 v89, v150
	v_mov_b32_e32 v90, v150
	v_mov_b32_e32 v91, v150
	v_mov_b32_e32 v92, v150
	v_mov_b32_e32 v93, v150
	v_mov_b32_e32 v94, v150
	v_mov_b32_e32 v95, v150
	v_mov_b32_e32 v104, v150
	v_mov_b32_e32 v105, v150
	v_mov_b32_e32 v106, v150
	v_mov_b32_e32 v107, v150
	v_mov_b32_e32 v108, v150
	v_mov_b32_e32 v109, v150
	v_mov_b32_e32 v110, v150
	v_mov_b32_e32 v111, v150
	v_mov_b32_e32 v120, v150
	v_mov_b32_e32 v121, v150
	v_mov_b32_e32 v122, v150
	v_mov_b32_e32 v123, v150
	v_mov_b32_e32 v124, v150
	v_mov_b32_e32 v125, v150
	v_mov_b32_e32 v126, v150
	v_mov_b32_e32 v127, v150
	s_branch .Lz643_mid

.Lz643_mid:
	s_waitcnt vmcnt(8)
	s_waitcnt lgkmcnt(0)
	s_setprio 1
	s_barrier
	v_mfma_f32_16x16x32_bf16 v[124:127], v[140:143], v[178:181], v[124:127]
	v_mfma_f32_16x16x32_bf16 v[120:123], v[154:157], v[178:181], v[120:123]
	v_mfma_f32_16x16x32_bf16 v[108:111], v[140:143], v[186:189], v[108:111]
	v_mfma_f32_16x16x32_bf16 v[104:107], v[154:157], v[186:189], v[104:107]
	v_mfma_f32_16x16x32_bf16 v[92:95], v[140:143], v[194:197], v[92:95]
	v_mfma_f32_16x16x32_bf16 v[88:91], v[154:157], v[194:197], v[88:91]
	v_mfma_f32_16x16x32_bf16 v[76:79], v[140:143], v[206:209], v[76:79]
	v_mfma_f32_16x16x32_bf16 v[72:75], v[154:157], v[206:209], v[72:75]
	v_mfma_f32_16x16x32_bf16 v[124:127], v[144:147], v[182:185], v[124:127]
	v_mfma_f32_16x16x32_bf16 v[120:123], v[158:161], v[182:185], v[120:123]
	v_mfma_f32_16x16x32_bf16 v[108:111], v[144:147], v[190:193], v[108:111]
	v_mfma_f32_16x16x32_bf16 v[104:107], v[158:161], v[190:193], v[104:107]
	v_mfma_f32_16x16x32_bf16 v[92:95], v[144:147], v[202:205], v[92:95]
	v_mfma_f32_16x16x32_bf16 v[88:91], v[158:161], v[202:205], v[88:91]
	v_mfma_f32_16x16x32_bf16 v[76:79], v[144:147], v[212:215], v[76:79]
	v_mfma_f32_16x16x32_bf16 v[72:75], v[158:161], v[212:215], v[72:75]
	s_setprio 0
	s_setprio 1
	v_mfma_f32_16x16x32_bf16 v[116:119], v[162:165], v[178:181], v[116:119]
	v_mfma_f32_16x16x32_bf16 v[112:115], v[170:173], v[178:181], v[112:115]
	v_mfma_f32_16x16x32_bf16 v[100:103], v[162:165], v[186:189], v[100:103]
	v_mfma_f32_16x16x32_bf16 v[96:99], v[170:173], v[186:189], v[96:99]
	v_mfma_f32_16x16x32_bf16 v[84:87], v[162:165], v[194:197], v[84:87]
	v_mfma_f32_16x16x32_bf16 v[80:83], v[170:173], v[194:197], v[80:83]
	v_mfma_f32_16x16x32_bf16 v[68:71], v[162:165], v[206:209], v[68:71]
	v_mfma_f32_16x16x32_bf16 v[64:67], v[170:173], v[206:209], v[64:67]
	v_mfma_f32_16x16x32_bf16 v[116:119], v[166:169], v[182:185], v[116:119]
	v_mfma_f32_16x16x32_bf16 v[112:115], v[174:177], v[182:185], v[112:115]
	v_mfma_f32_16x16x32_bf16 v[100:103], v[166:169], v[190:193], v[100:103]
	v_mfma_f32_16x16x32_bf16 v[96:99], v[174:177], v[190:193], v[96:99]
	v_mfma_f32_16x16x32_bf16 v[84:87], v[166:169], v[202:205], v[84:87]
	v_mfma_f32_16x16x32_bf16 v[80:83], v[174:177], v[202:205], v[80:83]
	v_mfma_f32_16x16x32_bf16 v[68:71], v[166:169], v[212:215], v[68:71]
	v_mfma_f32_16x16x32_bf16 v[64:67], v[174:177], v[212:215], v[64:67]
	s_barrier
	s_setprio 0
	s_add_i32 s50, s50, s35
	v_lshl_add_u64 v[148:149], s[6:7], 0, v[130:131]
	s_mov_b32 m0, s50
	ds_read_b128 v[178:181], v152 offset:16384
	ds_read_b128 v[182:185], v152 offset:17408
	ds_read_b128 v[186:189], v152 offset:18432
	ds_read_b128 v[190:193], v152 offset:19456
	ds_read_b128 v[194:197], v152 offset:20480
	ds_read_b128 v[202:205], v152 offset:21504
	ds_read_b128 v[206:209], v152 offset:22528
	ds_read_b128 v[212:215], v152 offset:23552
	global_load_lds_dwordx4 v[148:149], off
	s_add_i32 m0, s50, 0x2000
	s_add_u32 s50, s6, 0x80000
	v_lshl_add_u64 v[198:199], s[6:7], 0, v[134:135]
	s_addc_u32 s51, s7, 0
	s_add_i32 s53, s53, s35
	global_load_lds_dwordx4 v[198:199], off
	v_lshl_add_u64 v[216:217], s[50:51], 0, v[130:131]
	s_mov_b32 m0, s53
	v_lshl_add_u64 v[218:219], s[8:9], 0, v[132:133]
	global_load_lds_dwordx4 v[216:217], off
	v_lshl_add_u64 v[216:217], s[50:51], 0, v[134:135]
	s_add_i32 m0, s53, 0x2000
	s_nop 0
	global_load_lds_dwordx4 v[216:217], off
	v_lshl_add_u64 v[216:217], s[8:9], 0, v[128:129]
	s_mov_b32 m0, s11
	s_nop 0
	global_load_lds_dwordx4 v[216:217], off
	s_mov_b32 m0, s36
	s_nop 0
	global_load_lds_dwordx4 v[218:219], off
	s_waitcnt vmcnt(8)
	s_waitcnt lgkmcnt(0)
	s_setprio 1
	s_barrier
	v_mfma_f32_16x16x32_bf16 v[60:63], v[140:143], v[178:181], v[60:63]
	v_mfma_f32_16x16x32_bf16 v[56:59], v[154:157], v[178:181], v[56:59]
	v_mfma_f32_16x16x32_bf16 v[44:47], v[140:143], v[186:189], v[44:47]
	v_mfma_f32_16x16x32_bf16 v[40:43], v[154:157], v[186:189], v[40:43]
	v_mfma_f32_16x16x32_bf16 v[28:31], v[140:143], v[194:197], v[28:31]
	v_mfma_f32_16x16x32_bf16 v[24:27], v[154:157], v[194:197], v[24:27]
	v_mfma_f32_16x16x32_bf16 v[12:15], v[140:143], v[206:209], v[12:15]
	v_mfma_f32_16x16x32_bf16 v[8:11], v[154:157], v[206:209], v[8:11]
	v_mfma_f32_16x16x32_bf16 v[60:63], v[144:147], v[182:185], v[60:63]
	v_mfma_f32_16x16x32_bf16 v[56:59], v[158:161], v[182:185], v[56:59]
	v_mfma_f32_16x16x32_bf16 v[44:47], v[144:147], v[190:193], v[44:47]
	v_mfma_f32_16x16x32_bf16 v[40:43], v[158:161], v[190:193], v[40:43]
	v_mfma_f32_16x16x32_bf16 v[28:31], v[144:147], v[202:205], v[28:31]
	v_mfma_f32_16x16x32_bf16 v[24:27], v[158:161], v[202:205], v[24:27]
	v_mfma_f32_16x16x32_bf16 v[12:15], v[144:147], v[212:215], v[12:15]
	v_mfma_f32_16x16x32_bf16 v[8:11], v[158:161], v[212:215], v[8:11]
	s_setprio 0
	s_setprio 1
	v_mfma_f32_16x16x32_bf16 v[52:55], v[162:165], v[178:181], v[52:55]
	v_mfma_f32_16x16x32_bf16 v[48:51], v[170:173], v[178:181], v[48:51]
	v_mfma_f32_16x16x32_bf16 v[36:39], v[162:165], v[186:189], v[36:39]
	v_mfma_f32_16x16x32_bf16 v[32:35], v[170:173], v[186:189], v[32:35]
	v_mfma_f32_16x16x32_bf16 v[20:23], v[162:165], v[194:197], v[20:23]
	v_mfma_f32_16x16x32_bf16 v[16:19], v[170:173], v[194:197], v[16:19]
	v_mfma_f32_16x16x32_bf16 v[4:7], v[162:165], v[206:209], v[4:7]
	v_mfma_f32_16x16x32_bf16 v[0:3], v[170:173], v[206:209], v[0:3]
	v_mfma_f32_16x16x32_bf16 v[52:55], v[166:169], v[182:185], v[52:55]
	v_mfma_f32_16x16x32_bf16 v[48:51], v[174:177], v[182:185], v[48:51]
	v_mfma_f32_16x16x32_bf16 v[36:39], v[166:169], v[190:193], v[36:39]
	v_mfma_f32_16x16x32_bf16 v[32:35], v[174:177], v[190:193], v[32:35]
	v_mfma_f32_16x16x32_bf16 v[20:23], v[166:169], v[202:205], v[20:23]
	v_mfma_f32_16x16x32_bf16 v[16:19], v[174:177], v[202:205], v[16:19]
	v_mfma_f32_16x16x32_bf16 v[4:7], v[166:169], v[212:215], v[4:7]
	v_mfma_f32_16x16x32_bf16 v[0:3], v[174:177], v[212:215], v[0:3]
	s_barrier
	s_setprio 0
	s_add_i32 s50, 0, 0x18000
	v_add_u32_e32 v153, s50, v151
	s_add_i32 s51, 0, 0x1c000
	ds_read_b128 v[140:143], v153
	ds_read_b128 v[144:147], v153 offset:1024
	ds_read_b128 v[154:157], v153 offset:2048
	ds_read_b128 v[158:161], v153 offset:3072
	v_add_u32_e32 v153, s51, v151
	ds_read_b128 v[162:165], v153
	ds_read_b128 v[166:169], v153 offset:1024
	ds_read_b128 v[170:173], v153 offset:2048
	ds_read_b128 v[174:177], v153 offset:3072
	s_add_u32 s8, s8, 0x80000
	s_addc_u32 s9, s9, 0
	s_mov_b32 m0, s37
	v_lshl_add_u64 v[220:221], s[8:9], 0, v[128:129]
	ds_read_b128 v[178:181], v152 offset:32768
	ds_read_b128 v[182:185], v152 offset:33792
	ds_read_b128 v[186:189], v152 offset:34816
	ds_read_b128 v[190:193], v152 offset:35840
	ds_read_b128 v[194:197], v152 offset:36864
	ds_read_b128 v[202:205], v152 offset:37888
	ds_read_b128 v[206:209], v152 offset:38912
	ds_read_b128 v[212:215], v152 offset:39936
	global_load_lds_dwordx4 v[220:221], off
	v_lshl_add_u64 v[220:221], s[8:9], 0, v[132:133]
	s_mov_b32 m0, s38
	s_nop 0
	global_load_lds_dwordx4 v[220:221], off
	s_waitcnt vmcnt(8)
	s_waitcnt lgkmcnt(0)
	s_setprio 1
	s_barrier
	v_mfma_f32_16x16x32_bf16 v[124:127], v[140:143], v[178:181], v[124:127]
	v_mfma_f32_16x16x32_bf16 v[120:123], v[154:157], v[178:181], v[120:123]
	v_mfma_f32_16x16x32_bf16 v[108:111], v[140:143], v[186:189], v[108:111]
	v_mfma_f32_16x16x32_bf16 v[104:107], v[154:157], v[186:189], v[104:107]
	v_mfma_f32_16x16x32_bf16 v[92:95], v[140:143], v[194:197], v[92:95]
	v_mfma_f32_16x16x32_bf16 v[88:91], v[154:157], v[194:197], v[88:91]
	v_mfma_f32_16x16x32_bf16 v[76:79], v[140:143], v[206:209], v[76:79]
	v_mfma_f32_16x16x32_bf16 v[72:75], v[154:157], v[206:209], v[72:75]
	v_mfma_f32_16x16x32_bf16 v[124:127], v[144:147], v[182:185], v[124:127]
	v_mfma_f32_16x16x32_bf16 v[120:123], v[158:161], v[182:185], v[120:123]
	v_mfma_f32_16x16x32_bf16 v[108:111], v[144:147], v[190:193], v[108:111]
	v_mfma_f32_16x16x32_bf16 v[104:107], v[158:161], v[190:193], v[104:107]
	v_mfma_f32_16x16x32_bf16 v[92:95], v[144:147], v[202:205], v[92:95]
	v_mfma_f32_16x16x32_bf16 v[88:91], v[158:161], v[202:205], v[88:91]
	v_mfma_f32_16x16x32_bf16 v[76:79], v[144:147], v[212:215], v[76:79]
	v_mfma_f32_16x16x32_bf16 v[72:75], v[158:161], v[212:215], v[72:75]
	s_setprio 0
	s_setprio 1
	v_mfma_f32_16x16x32_bf16 v[116:119], v[162:165], v[178:181], v[116:119]
	v_mfma_f32_16x16x32_bf16 v[112:115], v[170:173], v[178:181], v[112:115]
	v_mfma_f32_16x16x32_bf16 v[100:103], v[162:165], v[186:189], v[100:103]
	v_mfma_f32_16x16x32_bf16 v[96:99], v[170:173], v[186:189], v[96:99]
	v_mfma_f32_16x16x32_bf16 v[84:87], v[162:165], v[194:197], v[84:87]
	v_mfma_f32_16x16x32_bf16 v[80:83], v[170:173], v[194:197], v[80:83]
	v_mfma_f32_16x16x32_bf16 v[68:71], v[162:165], v[206:209], v[68:71]
	v_mfma_f32_16x16x32_bf16 v[64:67], v[170:173], v[206:209], v[64:67]
	v_mfma_f32_16x16x32_bf16 v[116:119], v[166:169], v[182:185], v[116:119]
	v_mfma_f32_16x16x32_bf16 v[112:115], v[174:177], v[182:185], v[112:115]
	v_mfma_f32_16x16x32_bf16 v[100:103], v[166:169], v[190:193], v[100:103]
	v_mfma_f32_16x16x32_bf16 v[96:99], v[174:177], v[190:193], v[96:99]
	v_mfma_f32_16x16x32_bf16 v[84:87], v[166:169], v[202:205], v[84:87]
	v_mfma_f32_16x16x32_bf16 v[80:83], v[174:177], v[202:205], v[80:83]
	v_mfma_f32_16x16x32_bf16 v[68:71], v[166:169], v[212:215], v[68:71]
	v_mfma_f32_16x16x32_bf16 v[64:67], v[174:177], v[212:215], v[64:67]
	s_barrier
	s_setprio 0
	s_add_i32 s8, s50, s35
	v_lshl_add_u64 v[148:149], v[148:149], 0, s[64:65]
	s_mov_b32 m0, s8
	ds_read_b128 v[178:181], v152 offset:49152
	ds_read_b128 v[182:185], v152 offset:50176
	ds_read_b128 v[186:189], v152 offset:51200
	ds_read_b128 v[190:193], v152 offset:52224
	ds_read_b128 v[194:197], v152 offset:53248
	ds_read_b128 v[202:205], v152 offset:54272
	ds_read_b128 v[206:209], v152 offset:55296
	ds_read_b128 v[212:215], v152 offset:56320
	global_load_lds_dwordx4 v[148:149], off
	s_add_i32 m0, s8, 0x2000
	s_add_u32 s6, s6, 0x80080
	v_lshl_add_u64 v[148:149], v[198:199], 0, s[64:65]
	s_addc_u32 s7, s7, 0
	s_add_i32 s8, s51, s35
	global_load_lds_dwordx4 v[148:149], off
	v_lshl_add_u64 v[148:149], s[6:7], 0, v[130:131]
	s_mov_b32 m0, s8
	s_nop 0
	global_load_lds_dwordx4 v[148:149], off
	v_lshl_add_u64 v[148:149], s[6:7], 0, v[134:135]
	s_add_i32 m0, s8, 0x2000
	s_nop 0
	global_load_lds_dwordx4 v[148:149], off
	v_lshl_add_u64 v[148:149], v[216:217], 0, s[64:65]
	s_mov_b32 m0, s40
	s_nop 0
	global_load_lds_dwordx4 v[148:149], off
	v_lshl_add_u64 v[148:149], v[218:219], 0, s[64:65]
	s_mov_b32 m0, s41
	s_nop 0
	global_load_lds_dwordx4 v[148:149], off
	s_waitcnt vmcnt(8)
	s_waitcnt lgkmcnt(0)
	s_setprio 1
	s_barrier
	v_mfma_f32_16x16x32_bf16 v[60:63], v[140:143], v[178:181], v[60:63]
	v_mfma_f32_16x16x32_bf16 v[56:59], v[154:157], v[178:181], v[56:59]
	v_mfma_f32_16x16x32_bf16 v[44:47], v[140:143], v[186:189], v[44:47]
	v_mfma_f32_16x16x32_bf16 v[40:43], v[154:157], v[186:189], v[40:43]
	v_mfma_f32_16x16x32_bf16 v[28:31], v[140:143], v[194:197], v[28:31]
	v_mfma_f32_16x16x32_bf16 v[24:27], v[154:157], v[194:197], v[24:27]
	v_mfma_f32_16x16x32_bf16 v[12:15], v[140:143], v[206:209], v[12:15]
	v_mfma_f32_16x16x32_bf16 v[8:11], v[154:157], v[206:209], v[8:11]
	v_mfma_f32_16x16x32_bf16 v[60:63], v[144:147], v[182:185], v[60:63]
	v_mfma_f32_16x16x32_bf16 v[56:59], v[158:161], v[182:185], v[56:59]
	v_mfma_f32_16x16x32_bf16 v[44:47], v[144:147], v[190:193], v[44:47]
	v_mfma_f32_16x16x32_bf16 v[40:43], v[158:161], v[190:193], v[40:43]
	v_mfma_f32_16x16x32_bf16 v[28:31], v[144:147], v[202:205], v[28:31]
	v_mfma_f32_16x16x32_bf16 v[24:27], v[158:161], v[202:205], v[24:27]
	v_mfma_f32_16x16x32_bf16 v[12:15], v[144:147], v[212:215], v[12:15]
	v_mfma_f32_16x16x32_bf16 v[8:11], v[158:161], v[212:215], v[8:11]
	s_setprio 0
	s_setprio 1
	v_mfma_f32_16x16x32_bf16 v[52:55], v[162:165], v[178:181], v[52:55]
	v_mfma_f32_16x16x32_bf16 v[48:51], v[170:173], v[178:181], v[48:51]
	v_mfma_f32_16x16x32_bf16 v[36:39], v[162:165], v[186:189], v[36:39]
	v_mfma_f32_16x16x32_bf16 v[32:35], v[170:173], v[186:189], v[32:35]
	v_mfma_f32_16x16x32_bf16 v[20:23], v[162:165], v[194:197], v[20:23]
	v_mfma_f32_16x16x32_bf16 v[16:19], v[170:173], v[194:197], v[16:19]
	v_mfma_f32_16x16x32_bf16 v[4:7], v[162:165], v[206:209], v[4:7]
	v_mfma_f32_16x16x32_bf16 v[0:3], v[170:173], v[206:209], v[0:3]
	v_mfma_f32_16x16x32_bf16 v[52:55], v[166:169], v[182:185], v[52:55]
	v_mfma_f32_16x16x32_bf16 v[48:51], v[174:177], v[182:185], v[48:51]
	v_mfma_f32_16x16x32_bf16 v[36:39], v[166:169], v[190:193], v[36:39]
	v_mfma_f32_16x16x32_bf16 v[32:35], v[174:177], v[190:193], v[32:35]
	v_mfma_f32_16x16x32_bf16 v[20:23], v[166:169], v[202:205], v[20:23]
	v_mfma_f32_16x16x32_bf16 v[16:19], v[174:177], v[202:205], v[16:19]
	v_mfma_f32_16x16x32_bf16 v[4:7], v[166:169], v[212:215], v[4:7]
	v_mfma_f32_16x16x32_bf16 v[0:3], v[174:177], v[212:215], v[0:3]
	s_barrier
	s_setprio 0
	s_add_i32 s49, s49, 2
	s_add_u32 s4, s4, 0x100
	s_addc_u32 s5, s5, 0
	s_add_u32 s42, s42, 0x100
	s_addc_u32 s43, s43, 0
	s_cmp_gt_u32 s49, 29
	s_cbranch_scc0 .LBB0_643
	s_and_b64 vcc, exec, s[18:19]
	s_cbranch_vccz .LBB0_646
	s_barrier

.LBB0_973:
	s_add_u32 s4, s70, 0x80
	s_addc_u32 s5, s71, 0
	s_add_u32 s70, s68, 0x100
	s_addc_u32 s71, s69, 0
	s_mov_b32 s68, 0
	s_waitcnt lgkmcnt(0)
	s_add_i32 s88, s68, 2
	s_add_u32 s89, s4, 0x80
	s_addc_u32 s69, s5, 0
	s_add_i32 s92, 0, 0x10000
	s_cmp_eq_u32 s84, s68
	s_cselect_b32 s69, s63, s69
	s_cselect_b32 s68, s62, s89
	s_cselect_b32 s91, s67, s71
	s_cselect_b32 s90, s66, s70
	s_add_i32 s89, 0, 0x14000
	v_add_u32_e32 v152, s92, v181
	v_add_u32_e32 v168, s89, v181
	ds_read_b128 v[128:131], v152
	ds_read_b128 v[132:135], v152 offset:1024
	ds_read_b128 v[136:139], v152 offset:2048
	ds_read_b128 v[152:155], v152 offset:3072
	ds_read_b128 v[156:159], v168
	ds_read_b128 v[160:163], v168 offset:1024
	ds_read_b128 v[164:167], v168 offset:2048
	ds_read_b128 v[168:171], v168 offset:3072
	v_lshl_add_u64 v[212:213], s[4:5], 0, v[148:149]
	s_add_i32 m0, s76, 0xc000
	ds_read_b128 v[172:175], v182
	ds_read_b128 v[176:179], v182 offset:1024
	ds_read_b128 v[184:187], v182 offset:2048
	ds_read_b128 v[188:191], v182 offset:3072
	ds_read_b128 v[192:195], v182 offset:4096
	ds_read_b128 v[196:199], v182 offset:5120
	ds_read_b128 v[202:205], v182 offset:6144
	ds_read_b128 v[206:209], v182 offset:7168
	global_load_lds_dwordx4 v[212:213], off
	v_lshl_add_u64 v[212:213], s[4:5], 0, v[150:151]
	s_add_i32 m0, s76, 0xe000
	s_nop 0
	global_load_lds_dwordx4 v[212:213], off
	v_mov_b32_e32 v0, v180
	v_mov_b32_e32 v1, v180
	v_mov_b32_e32 v2, v180
	v_mov_b32_e32 v3, v180
	v_mov_b32_e32 v4, v180
	v_mov_b32_e32 v5, v180
	v_mov_b32_e32 v6, v180
	v_mov_b32_e32 v7, v180
	v_mov_b32_e32 v8, v180
	v_mov_b32_e32 v9, v180
	v_mov_b32_e32 v10, v180
	v_mov_b32_e32 v11, v180
	v_mov_b32_e32 v12, v180
	v_mov_b32_e32 v13, v180
	v_mov_b32_e32 v14, v180
	v_mov_b32_e32 v15, v180
	v_mov_b32_e32 v16, v180
	v_mov_b32_e32 v17, v180
	v_mov_b32_e32 v18, v180
	v_mov_b32_e32 v19, v180
	v_mov_b32_e32 v20, v180
	v_mov_b32_e32 v21, v180
	v_mov_b32_e32 v22, v180
	v_mov_b32_e32 v23, v180
	v_mov_b32_e32 v24, v180
	v_mov_b32_e32 v25, v180
	v_mov_b32_e32 v26, v180
	v_mov_b32_e32 v27, v180
	v_mov_b32_e32 v28, v180
	v_mov_b32_e32 v29, v180
	v_mov_b32_e32 v30, v180
	v_mov_b32_e32 v31, v180
	v_mov_b32_e32 v32, v180
	v_mov_b32_e32 v33, v180
	v_mov_b32_e32 v34, v180
	v_mov_b32_e32 v35, v180
	v_mov_b32_e32 v36, v180
	v_mov_b32_e32 v37, v180
	v_mov_b32_e32 v38, v180
	v_mov_b32_e32 v39, v180
	v_mov_b32_e32 v40, v180
	v_mov_b32_e32 v41, v180
	v_mov_b32_e32 v42, v180
	v_mov_b32_e32 v43, v180
	v_mov_b32_e32 v44, v180
	v_mov_b32_e32 v45, v180
	v_mov_b32_e32 v46, v180
	v_mov_b32_e32 v47, v180
	v_mov_b32_e32 v48, v180
	v_mov_b32_e32 v49, v180
	v_mov_b32_e32 v50, v180
	v_mov_b32_e32 v51, v180
	v_mov_b32_e32 v52, v180
	v_mov_b32_e32 v53, v180
	v_mov_b32_e32 v54, v180
	v_mov_b32_e32 v55, v180
	v_mov_b32_e32 v56, v180
	v_mov_b32_e32 v57, v180
	v_mov_b32_e32 v58, v180
	v_mov_b32_e32 v59, v180
	v_mov_b32_e32 v60, v180
	v_mov_b32_e32 v61, v180
	v_mov_b32_e32 v62, v180
	v_mov_b32_e32 v63, v180
	v_mov_b32_e32 v64, v180
	v_mov_b32_e32 v65, v180
	v_mov_b32_e32 v66, v180
	v_mov_b32_e32 v67, v180
	v_mov_b32_e32 v68, v180
	v_mov_b32_e32 v69, v180
	v_mov_b32_e32 v70, v180
	v_mov_b32_e32 v71, v180
	v_mov_b32_e32 v72, v180
	v_mov_b32_e32 v73, v180
	v_mov_b32_e32 v74, v180
	v_mov_b32_e32 v75, v180
	v_mov_b32_e32 v76, v180
	v_mov_b32_e32 v77, v180
	v_mov_b32_e32 v78, v180
	v_mov_b32_e32 v79, v180
	v_mov_b32_e32 v80, v180
	v_mov_b32_e32 v81, v180
	v_mov_b32_e32 v82, v180
	v_mov_b32_e32 v83, v180
	v_mov_b32_e32 v84, v180
	v_mov_b32_e32 v85, v180
	v_mov_b32_e32 v86, v180
	v_mov_b32_e32 v87, v180
	v_mov_b32_e32 v88, v180
	v_mov_b32_e32 v89, v180
	v_mov_b32_e32 v90, v180
	v_mov_b32_e32 v91, v180
	v_mov_b32_e32 v92, v180
	v_mov_b32_e32 v93, v180
	v_mov_b32_e32 v94, v180
	v_mov_b32_e32 v95, v180
	v_mov_b32_e32 v96, v180
	v_mov_b32_e32 v97, v180
	v_mov_b32_e32 v98, v180
	v_mov_b32_e32 v99, v180
	v_mov_b32_e32 v100, v180
	v_mov_b32_e32 v101, v180
	v_mov_b32_e32 v102, v180
	v_mov_b32_e32 v103, v180
	v_mov_b32_e32 v104, v180
	v_mov_b32_e32 v105, v180
	v_mov_b32_e32 v106, v180
	v_mov_b32_e32 v107, v180
	v_mov_b32_e32 v108, v180
	v_mov_b32_e32 v109, v180
	v_mov_b32_e32 v110, v180
	v_mov_b32_e32 v111, v180
	v_mov_b32_e32 v112, v180
	v_mov_b32_e32 v113, v180
	v_mov_b32_e32 v114, v180
	v_mov_b32_e32 v115, v180
	v_mov_b32_e32 v116, v180
	v_mov_b32_e32 v117, v180
	v_mov_b32_e32 v118, v180
	v_mov_b32_e32 v119, v180
	v_mov_b32_e32 v120, v180
	v_mov_b32_e32 v121, v180
	v_mov_b32_e32 v122, v180
	v_mov_b32_e32 v123, v180
	v_mov_b32_e32 v124, v180
	v_mov_b32_e32 v125, v180
	v_mov_b32_e32 v126, v180
	v_mov_b32_e32 v127, v180
	s_branch .Lz974_mid

.Lz974_mid:
	s_waitcnt vmcnt(8)
	s_waitcnt lgkmcnt(0)
	s_setprio 1
	s_barrier
	v_mfma_f32_16x16x32_bf16 v[124:127], v[128:131], v[172:175], v[124:127]
	v_mfma_f32_16x16x32_bf16 v[120:123], v[136:139], v[172:175], v[120:123]
	v_mfma_f32_16x16x32_bf16 v[116:119], v[128:131], v[184:187], v[116:119]
	v_mfma_f32_16x16x32_bf16 v[112:115], v[136:139], v[184:187], v[112:115]
	v_mfma_f32_16x16x32_bf16 v[108:111], v[128:131], v[192:195], v[108:111]
	v_mfma_f32_16x16x32_bf16 v[104:107], v[136:139], v[192:195], v[104:107]
	v_mfma_f32_16x16x32_bf16 v[100:103], v[128:131], v[202:205], v[100:103]
	v_mfma_f32_16x16x32_bf16 v[96:99], v[136:139], v[202:205], v[96:99]
	v_mfma_f32_16x16x32_bf16 v[124:127], v[132:135], v[176:179], v[124:127]
	v_mfma_f32_16x16x32_bf16 v[120:123], v[152:155], v[176:179], v[120:123]
	v_mfma_f32_16x16x32_bf16 v[116:119], v[132:135], v[188:191], v[116:119]
	v_mfma_f32_16x16x32_bf16 v[112:115], v[152:155], v[188:191], v[112:115]
	v_mfma_f32_16x16x32_bf16 v[108:111], v[132:135], v[196:199], v[108:111]
	v_mfma_f32_16x16x32_bf16 v[104:107], v[152:155], v[196:199], v[104:107]
	v_mfma_f32_16x16x32_bf16 v[100:103], v[132:135], v[206:209], v[100:103]
	v_mfma_f32_16x16x32_bf16 v[96:99], v[152:155], v[206:209], v[96:99]
	s_setprio 0
	s_setprio 1
	v_mfma_f32_16x16x32_bf16 v[92:95], v[156:159], v[172:175], v[92:95]
	v_mfma_f32_16x16x32_bf16 v[88:91], v[164:167], v[172:175], v[88:91]
	v_mfma_f32_16x16x32_bf16 v[84:87], v[156:159], v[184:187], v[84:87]
	v_mfma_f32_16x16x32_bf16 v[80:83], v[164:167], v[184:187], v[80:83]
	v_mfma_f32_16x16x32_bf16 v[76:79], v[156:159], v[192:195], v[76:79]
	v_mfma_f32_16x16x32_bf16 v[72:75], v[164:167], v[192:195], v[72:75]
	v_mfma_f32_16x16x32_bf16 v[68:71], v[156:159], v[202:205], v[68:71]
	v_mfma_f32_16x16x32_bf16 v[64:67], v[164:167], v[202:205], v[64:67]
	v_mfma_f32_16x16x32_bf16 v[92:95], v[160:163], v[176:179], v[92:95]
	v_mfma_f32_16x16x32_bf16 v[88:91], v[168:171], v[176:179], v[88:91]
	v_mfma_f32_16x16x32_bf16 v[84:87], v[160:163], v[188:191], v[84:87]
	v_mfma_f32_16x16x32_bf16 v[80:83], v[168:171], v[188:191], v[80:83]
	v_mfma_f32_16x16x32_bf16 v[76:79], v[160:163], v[196:199], v[76:79]
	v_mfma_f32_16x16x32_bf16 v[72:75], v[168:171], v[196:199], v[72:75]
	v_mfma_f32_16x16x32_bf16 v[68:71], v[160:163], v[206:209], v[68:71]
	v_mfma_f32_16x16x32_bf16 v[64:67], v[168:171], v[206:209], v[64:67]
	s_barrier
	s_setprio 0
	s_add_i32 s92, s92, s72
	v_lshl_add_u64 v[212:213], s[90:91], 0, v[142:143]
	s_mov_b32 m0, s92
	ds_read_b128 v[172:175], v182 offset:16384
	ds_read_b128 v[176:179], v182 offset:17408
	ds_read_b128 v[184:187], v182 offset:18432
	ds_read_b128 v[188:191], v182 offset:19456
	ds_read_b128 v[192:195], v182 offset:20480
	ds_read_b128 v[196:199], v182 offset:21504
	ds_read_b128 v[202:205], v182 offset:22528
	ds_read_b128 v[206:209], v182 offset:23552
	global_load_lds_dwordx4 v[212:213], off
	s_add_i32 m0, s92, 0x2000
	v_lshl_add_u64 v[214:215], s[90:91], 0, v[146:147]
	s_add_u32 s90, s90, s56
	s_addc_u32 s91, s91, 0
	s_add_i32 s89, s89, s72
	global_load_lds_dwordx4 v[214:215], off
	v_lshl_add_u64 v[216:217], s[90:91], 0, v[142:143]
	s_mov_b32 m0, s89
	v_lshl_add_u64 v[218:219], s[90:91], 0, v[146:147]
	global_load_lds_dwordx4 v[216:217], off
	s_add_i32 m0, s89, 0x2000
	v_lshl_add_u64 v[220:221], s[68:69], 0, v[140:141]
	global_load_lds_dwordx4 v[218:219], off
	s_mov_b32 m0, s76
	v_lshl_add_u64 v[222:223], s[68:69], 0, v[144:145]
	global_load_lds_dwordx4 v[220:221], off
	s_mov_b32 m0, s77
	s_nop 0
	global_load_lds_dwordx4 v[222:223], off
	s_waitcnt vmcnt(8)
	s_waitcnt lgkmcnt(0)
	s_setprio 1
	s_barrier
	v_mfma_f32_16x16x32_bf16 v[60:63], v[128:131], v[172:175], v[60:63]
	v_mfma_f32_16x16x32_bf16 v[56:59], v[136:139], v[172:175], v[56:59]
	v_mfma_f32_16x16x32_bf16 v[52:55], v[128:131], v[184:187], v[52:55]
	v_mfma_f32_16x16x32_bf16 v[48:51], v[136:139], v[184:187], v[48:51]
	v_mfma_f32_16x16x32_bf16 v[44:47], v[128:131], v[192:195], v[44:47]
	v_mfma_f32_16x16x32_bf16 v[40:43], v[136:139], v[192:195], v[40:43]
	v_mfma_f32_16x16x32_bf16 v[36:39], v[128:131], v[202:205], v[36:39]
	v_mfma_f32_16x16x32_bf16 v[32:35], v[136:139], v[202:205], v[32:35]
	v_mfma_f32_16x16x32_bf16 v[60:63], v[132:135], v[176:179], v[60:63]
	v_mfma_f32_16x16x32_bf16 v[56:59], v[152:155], v[176:179], v[56:59]
	v_mfma_f32_16x16x32_bf16 v[52:55], v[132:135], v[188:191], v[52:55]
	v_mfma_f32_16x16x32_bf16 v[48:51], v[152:155], v[188:191], v[48:51]
	v_mfma_f32_16x16x32_bf16 v[44:47], v[132:135], v[196:199], v[44:47]
	v_mfma_f32_16x16x32_bf16 v[40:43], v[152:155], v[196:199], v[40:43]
	v_mfma_f32_16x16x32_bf16 v[36:39], v[132:135], v[206:209], v[36:39]
	v_mfma_f32_16x16x32_bf16 v[32:35], v[152:155], v[206:209], v[32:35]
	s_setprio 0
	s_setprio 1
	v_mfma_f32_16x16x32_bf16 v[28:31], v[156:159], v[172:175], v[28:31]
	v_mfma_f32_16x16x32_bf16 v[24:27], v[164:167], v[172:175], v[24:27]
	v_mfma_f32_16x16x32_bf16 v[20:23], v[156:159], v[184:187], v[20:23]
	v_mfma_f32_16x16x32_bf16 v[16:19], v[164:167], v[184:187], v[16:19]
	v_mfma_f32_16x16x32_bf16 v[12:15], v[156:159], v[192:195], v[12:15]
	v_mfma_f32_16x16x32_bf16 v[8:11], v[164:167], v[192:195], v[8:11]
	v_mfma_f32_16x16x32_bf16 v[4:7], v[156:159], v[202:205], v[4:7]
	v_mfma_f32_16x16x32_bf16 v[0:3], v[164:167], v[202:205], v[0:3]
	v_mfma_f32_16x16x32_bf16 v[28:31], v[160:163], v[176:179], v[28:31]
	v_mfma_f32_16x16x32_bf16 v[24:27], v[168:171], v[176:179], v[24:27]
	v_mfma_f32_16x16x32_bf16 v[20:23], v[160:163], v[188:191], v[20:23]
	v_mfma_f32_16x16x32_bf16 v[16:19], v[168:171], v[188:191], v[16:19]
	v_mfma_f32_16x16x32_bf16 v[12:15], v[160:163], v[196:199], v[12:15]
	v_mfma_f32_16x16x32_bf16 v[8:11], v[168:171], v[196:199], v[8:11]
	v_mfma_f32_16x16x32_bf16 v[4:7], v[160:163], v[206:209], v[4:7]
	v_mfma_f32_16x16x32_bf16 v[0:3], v[168:171], v[206:209], v[0:3]
	s_barrier
	s_setprio 0
	s_add_i32 s89, 0, 0x18000
	s_add_i32 s90, 0, 0x1c000
	v_add_u32_e32 v152, s89, v181
	v_add_u32_e32 v168, s90, v181
	ds_read_b128 v[128:131], v152
	ds_read_b128 v[132:135], v152 offset:1024
	ds_read_b128 v[136:139], v152 offset:2048
	ds_read_b128 v[152:155], v152 offset:3072
	ds_read_b128 v[156:159], v168
	ds_read_b128 v[160:163], v168 offset:1024
	ds_read_b128 v[164:167], v168 offset:2048
	ds_read_b128 v[168:171], v168 offset:3072
	s_add_u32 s68, s68, s56
	s_addc_u32 s69, s69, 0
	s_mov_b32 m0, s78
	v_lshl_add_u64 v[224:225], s[68:69], 0, v[140:141]
	ds_read_b128 v[172:175], v182 offset:32768
	ds_read_b128 v[176:179], v182 offset:33792
	ds_read_b128 v[184:187], v182 offset:34816
	ds_read_b128 v[188:191], v182 offset:35840
	ds_read_b128 v[192:195], v182 offset:36864
	ds_read_b128 v[196:199], v182 offset:37888
	ds_read_b128 v[202:205], v182 offset:38912
	ds_read_b128 v[206:209], v182 offset:39936
	global_load_lds_dwordx4 v[224:225], off
	v_lshl_add_u64 v[224:225], s[68:69], 0, v[144:145]
	s_mov_b32 m0, s79
	s_nop 0
	global_load_lds_dwordx4 v[224:225], off
	s_waitcnt vmcnt(8)
	s_waitcnt lgkmcnt(0)
	s_setprio 1
	s_barrier
	v_mfma_f32_16x16x32_bf16 v[124:127], v[128:131], v[172:175], v[124:127]
	v_mfma_f32_16x16x32_bf16 v[120:123], v[136:139], v[172:175], v[120:123]
	v_mfma_f32_16x16x32_bf16 v[116:119], v[128:131], v[184:187], v[116:119]
	v_mfma_f32_16x16x32_bf16 v[112:115], v[136:139], v[184:187], v[112:115]
	v_mfma_f32_16x16x32_bf16 v[108:111], v[128:131], v[192:195], v[108:111]
	v_mfma_f32_16x16x32_bf16 v[104:107], v[136:139], v[192:195], v[104:107]
	v_mfma_f32_16x16x32_bf16 v[100:103], v[128:131], v[202:205], v[100:103]
	v_mfma_f32_16x16x32_bf16 v[96:99], v[136:139], v[202:205], v[96:99]
	v_mfma_f32_16x16x32_bf16 v[124:127], v[132:135], v[176:179], v[124:127]
	v_mfma_f32_16x16x32_bf16 v[120:123], v[152:155], v[176:179], v[120:123]
	v_mfma_f32_16x16x32_bf16 v[116:119], v[132:135], v[188:191], v[116:119]
	v_mfma_f32_16x16x32_bf16 v[112:115], v[152:155], v[188:191], v[112:115]
	v_mfma_f32_16x16x32_bf16 v[108:111], v[132:135], v[196:199], v[108:111]
	v_mfma_f32_16x16x32_bf16 v[104:107], v[152:155], v[196:199], v[104:107]
	v_mfma_f32_16x16x32_bf16 v[100:103], v[132:135], v[206:209], v[100:103]
	v_mfma_f32_16x16x32_bf16 v[96:99], v[152:155], v[206:209], v[96:99]
	s_setprio 0
	s_setprio 1
	v_mfma_f32_16x16x32_bf16 v[92:95], v[156:159], v[172:175], v[92:95]
	v_mfma_f32_16x16x32_bf16 v[88:91], v[164:167], v[172:175], v[88:91]
	v_mfma_f32_16x16x32_bf16 v[84:87], v[156:159], v[184:187], v[84:87]
	v_mfma_f32_16x16x32_bf16 v[80:83], v[164:167], v[184:187], v[80:83]
	v_mfma_f32_16x16x32_bf16 v[76:79], v[156:159], v[192:195], v[76:79]
	v_mfma_f32_16x16x32_bf16 v[72:75], v[164:167], v[192:195], v[72:75]
	v_mfma_f32_16x16x32_bf16 v[68:71], v[156:159], v[202:205], v[68:71]
	v_mfma_f32_16x16x32_bf16 v[64:67], v[164:167], v[202:205], v[64:67]
	v_mfma_f32_16x16x32_bf16 v[92:95], v[160:163], v[176:179], v[92:95]
	v_mfma_f32_16x16x32_bf16 v[88:91], v[168:171], v[176:179], v[88:91]
	v_mfma_f32_16x16x32_bf16 v[84:87], v[160:163], v[188:191], v[84:87]
	v_mfma_f32_16x16x32_bf16 v[80:83], v[168:171], v[188:191], v[80:83]
	v_mfma_f32_16x16x32_bf16 v[76:79], v[160:163], v[196:199], v[76:79]
	v_mfma_f32_16x16x32_bf16 v[72:75], v[168:171], v[196:199], v[72:75]
	v_mfma_f32_16x16x32_bf16 v[68:71], v[160:163], v[206:209], v[68:71]
	v_mfma_f32_16x16x32_bf16 v[64:67], v[168:171], v[206:209], v[64:67]
	s_barrier
	s_setprio 0
	s_add_i32 s68, s89, s72
	v_lshl_add_u64 v[212:213], v[212:213], 0, s[64:65]
	s_mov_b32 m0, s68
	ds_read_b128 v[172:175], v182 offset:49152
	ds_read_b128 v[176:179], v182 offset:50176
	ds_read_b128 v[184:187], v182 offset:51200
	ds_read_b128 v[188:191], v182 offset:52224
	ds_read_b128 v[192:195], v182 offset:53248
	ds_read_b128 v[196:199], v182 offset:54272
	ds_read_b128 v[202:205], v182 offset:55296
	ds_read_b128 v[206:209], v182 offset:56320
	global_load_lds_dwordx4 v[212:213], off
	v_lshl_add_u64 v[212:213], v[214:215], 0, s[64:65]
	s_add_i32 m0, s68, 0x2000
	s_add_i32 s68, s90, s72
	global_load_lds_dwordx4 v[212:213], off
	v_lshl_add_u64 v[212:213], v[216:217], 0, s[64:65]
	s_mov_b32 m0, s68
	s_nop 0
	global_load_lds_dwordx4 v[212:213], off
	v_lshl_add_u64 v[212:213], v[218:219], 0, s[64:65]
	s_add_i32 m0, s68, 0x2000
	s_nop 0
	global_load_lds_dwordx4 v[212:213], off
	v_lshl_add_u64 v[212:213], v[220:221], 0, s[64:65]
	s_mov_b32 m0, s82
	s_nop 0
	global_load_lds_dwordx4 v[212:213], off
	v_lshl_add_u64 v[212:213], v[222:223], 0, s[64:65]
	s_mov_b32 m0, s83
	s_nop 0
	global_load_lds_dwordx4 v[212:213], off
	s_waitcnt vmcnt(8)
	s_waitcnt lgkmcnt(0)
	s_setprio 1
	s_barrier
	v_mfma_f32_16x16x32_bf16 v[60:63], v[128:131], v[172:175], v[60:63]
	v_mfma_f32_16x16x32_bf16 v[56:59], v[136:139], v[172:175], v[56:59]
	v_mfma_f32_16x16x32_bf16 v[52:55], v[128:131], v[184:187], v[52:55]
	v_mfma_f32_16x16x32_bf16 v[48:51], v[136:139], v[184:187], v[48:51]
	v_mfma_f32_16x16x32_bf16 v[44:47], v[128:131], v[192:195], v[44:47]
	v_mfma_f32_16x16x32_bf16 v[40:43], v[136:139], v[192:195], v[40:43]
	v_mfma_f32_16x16x32_bf16 v[36:39], v[128:131], v[202:205], v[36:39]
	v_mfma_f32_16x16x32_bf16 v[32:35], v[136:139], v[202:205], v[32:35]
	v_mfma_f32_16x16x32_bf16 v[60:63], v[132:135], v[176:179], v[60:63]
	v_mfma_f32_16x16x32_bf16 v[56:59], v[152:155], v[176:179], v[56:59]
	v_mfma_f32_16x16x32_bf16 v[52:55], v[132:135], v[188:191], v[52:55]
	v_mfma_f32_16x16x32_bf16 v[48:51], v[152:155], v[188:191], v[48:51]
	v_mfma_f32_16x16x32_bf16 v[44:47], v[132:135], v[196:199], v[44:47]
	v_mfma_f32_16x16x32_bf16 v[40:43], v[152:155], v[196:199], v[40:43]
	v_mfma_f32_16x16x32_bf16 v[36:39], v[132:135], v[206:209], v[36:39]
	v_mfma_f32_16x16x32_bf16 v[32:35], v[152:155], v[206:209], v[32:35]
	s_setprio 0
	s_setprio 1
	v_mfma_f32_16x16x32_bf16 v[28:31], v[156:159], v[172:175], v[28:31]
	v_mfma_f32_16x16x32_bf16 v[24:27], v[164:167], v[172:175], v[24:27]
	v_mfma_f32_16x16x32_bf16 v[20:23], v[156:159], v[184:187], v[20:23]
	v_mfma_f32_16x16x32_bf16 v[16:19], v[164:167], v[184:187], v[16:19]
	v_mfma_f32_16x16x32_bf16 v[12:15], v[156:159], v[192:195], v[12:15]
	v_mfma_f32_16x16x32_bf16 v[8:11], v[164:167], v[192:195], v[8:11]
	v_mfma_f32_16x16x32_bf16 v[4:7], v[156:159], v[202:205], v[4:7]
	v_mfma_f32_16x16x32_bf16 v[0:3], v[164:167], v[202:205], v[0:3]
	v_mfma_f32_16x16x32_bf16 v[28:31], v[160:163], v[176:179], v[28:31]
	v_mfma_f32_16x16x32_bf16 v[24:27], v[168:171], v[176:179], v[24:27]
	v_mfma_f32_16x16x32_bf16 v[20:23], v[160:163], v[188:191], v[20:23]
	v_mfma_f32_16x16x32_bf16 v[16:19], v[168:171], v[188:191], v[16:19]
	v_mfma_f32_16x16x32_bf16 v[12:15], v[160:163], v[196:199], v[12:15]
	v_mfma_f32_16x16x32_bf16 v[8:11], v[168:171], v[196:199], v[8:11]
	v_mfma_f32_16x16x32_bf16 v[4:7], v[160:163], v[206:209], v[4:7]
	v_mfma_f32_16x16x32_bf16 v[0:3], v[168:171], v[206:209], v[0:3]
	s_barrier
	s_setprio 0
	s_add_u32 s4, s4, 0x100
	s_addc_u32 s5, s5, 0
	s_add_u32 s70, s70, 0x100
	s_addc_u32 s71, s71, 0
	s_cmp_ge_u32 s88, s80
	s_mov_b32 s68, s88
	s_cbranch_scc0 .LBB0_974
	s_and_b64 vcc, exec, s[18:19]
	s_cbranch_vccz .LBB0_977
	s_barrier

.LBB0_1101:
	s_ashr_i32 s25, s24, 31
	s_lshl_b64 s[26:27], s[24:25], 20
	s_add_u32 s26, s48, s26
	s_addc_u32 s27, s49, s27
	s_and_b64 s[28:29], s[2:3], exec
	s_cselect_b32 s25, s27, s5
	s_cselect_b32 s61, s26, s4
	s_ashr_i32 s23, s22, 31
	s_lshl_b64 s[28:29], s[22:23], 20
	s_add_u32 s28, s50, s28
	s_addc_u32 s29, s51, s29
	s_and_b64 s[36:37], s[2:3], exec
	s_cselect_b32 s23, s29, s35
	s_cselect_b32 s62, s28, s34
	s_add_u32 s4, s4, 0x80080
	s_addc_u32 s5, s5, 0
	s_add_u32 s63, s34, 0x100
	s_addc_u32 s66, s35, 0
	s_mov_b32 s67, -2
	s_add_u32 s34, s4, 0xfff80080
	s_addc_u32 s35, s5, -1
	s_add_i32 s68, 0, 0x10000
	s_cmp_eq_u32 s67, 28
	s_cselect_b32 s37, s25, s35
	s_cselect_b32 s36, s61, s34
	s_cselect_b32 s35, s23, s66
	s_cselect_b32 s34, s62, s63
	s_add_i32 s70, 0, 0x14000
	v_add_u32_e32 v84, s68, v173
	v_add_u32_e32 v108, s70, v173
	ds_read_b128 v[72:75], v84
	ds_read_b128 v[76:79], v84 offset:1024
	ds_read_b128 v[80:83], v84 offset:2048
	ds_read_b128 v[84:87], v84 offset:3072
	ds_read_b128 v[96:99], v108
	ds_read_b128 v[100:103], v108 offset:1024
	ds_read_b128 v[104:107], v108 offset:2048
	ds_read_b128 v[108:111], v108 offset:3072
	v_lshl_add_u64 v[170:171], s[4:5], 0, v[166:167]
	s_add_i32 m0, s31, 0xc000
	ds_read_b128 v[176:179], v174
	ds_read_b128 v[180:183], v174 offset:1024
	ds_read_b128 v[184:187], v174 offset:2048
	ds_read_b128 v[188:191], v174 offset:3072
	ds_read_b128 v[192:195], v174 offset:4096
	ds_read_b128 v[196:199], v174 offset:5120
	ds_read_b128 v[202:205], v174 offset:6144
	ds_read_b128 v[206:209], v174 offset:7168
	global_load_lds_dwordx4 v[170:171], off
	v_lshl_add_u64 v[170:171], s[4:5], 0, v[168:169]
	s_add_i32 m0, s31, 0xe000
	s_nop 0
	global_load_lds_dwordx4 v[170:171], off
	s_add_u32 vcc_lo, s4, 0xfff80000
	s_addc_u32 vcc_hi, s5, -1
	s_mov_b32 m0, s55
	s_nop 0
	global_load_lds_dwordx4 v164, vcc
	s_mov_b32 m0, s56
	s_nop 0
	global_load_lds_dwordx4 v162, vcc
	v_mov_b32_e32 v0, v172
	v_mov_b32_e32 v1, v172
	v_mov_b32_e32 v2, v172
	v_mov_b32_e32 v3, v172
	v_mov_b32_e32 v8, v172
	v_mov_b32_e32 v9, v172
	v_mov_b32_e32 v10, v172
	v_mov_b32_e32 v11, v172
	v_mov_b32_e32 v16, v172
	v_mov_b32_e32 v17, v172
	v_mov_b32_e32 v18, v172
	v_mov_b32_e32 v19, v172
	v_mov_b32_e32 v24, v172
	v_mov_b32_e32 v25, v172
	v_mov_b32_e32 v26, v172
	v_mov_b32_e32 v27, v172
	v_mov_b32_e32 v32, v172
	v_mov_b32_e32 v33, v172
	v_mov_b32_e32 v34, v172
	v_mov_b32_e32 v35, v172
	v_mov_b32_e32 v40, v172
	v_mov_b32_e32 v41, v172
	v_mov_b32_e32 v42, v172
	v_mov_b32_e32 v43, v172
	v_mov_b32_e32 v48, v172
	v_mov_b32_e32 v49, v172
	v_mov_b32_e32 v50, v172
	v_mov_b32_e32 v51, v172
	v_mov_b32_e32 v56, v172
	v_mov_b32_e32 v57, v172
	v_mov_b32_e32 v58, v172
	v_mov_b32_e32 v59, v172
	v_mov_b32_e32 v4, v172
	v_mov_b32_e32 v5, v172
	v_mov_b32_e32 v6, v172
	v_mov_b32_e32 v7, v172
	v_mov_b32_e32 v12, v172
	v_mov_b32_e32 v13, v172
	v_mov_b32_e32 v14, v172
	v_mov_b32_e32 v15, v172
	v_mov_b32_e32 v20, v172
	v_mov_b32_e32 v21, v172
	v_mov_b32_e32 v22, v172
	v_mov_b32_e32 v23, v172
	v_mov_b32_e32 v28, v172
	v_mov_b32_e32 v29, v172
	v_mov_b32_e32 v30, v172
	v_mov_b32_e32 v31, v172
	v_mov_b32_e32 v36, v172
	v_mov_b32_e32 v37, v172
	v_mov_b32_e32 v38, v172
	v_mov_b32_e32 v39, v172
	v_mov_b32_e32 v44, v172
	v_mov_b32_e32 v45, v172
	v_mov_b32_e32 v46, v172
	v_mov_b32_e32 v47, v172
	v_mov_b32_e32 v52, v172
	v_mov_b32_e32 v53, v172
	v_mov_b32_e32 v54, v172
	v_mov_b32_e32 v55, v172
	v_mov_b32_e32 v60, v172
	v_mov_b32_e32 v61, v172
	v_mov_b32_e32 v62, v172
	v_mov_b32_e32 v63, v172
	v_mov_b32_e32 v64, v172
	v_mov_b32_e32 v65, v172
	v_mov_b32_e32 v66, v172
	v_mov_b32_e32 v67, v172
	v_mov_b32_e32 v88, v172
	v_mov_b32_e32 v89, v172
	v_mov_b32_e32 v90, v172
	v_mov_b32_e32 v91, v172
	v_mov_b32_e32 v112, v172
	v_mov_b32_e32 v113, v172
	v_mov_b32_e32 v114, v172
	v_mov_b32_e32 v115, v172
	v_mov_b32_e32 v120, v172
	v_mov_b32_e32 v121, v172
	v_mov_b32_e32 v122, v172
	v_mov_b32_e32 v123, v172
	v_mov_b32_e32 v128, v172
	v_mov_b32_e32 v129, v172
	v_mov_b32_e32 v130, v172
	v_mov_b32_e32 v131, v172
	v_mov_b32_e32 v136, v172
	v_mov_b32_e32 v137, v172
	v_mov_b32_e32 v138, v172
	v_mov_b32_e32 v139, v172
	v_mov_b32_e32 v144, v172
	v_mov_b32_e32 v145, v172
	v_mov_b32_e32 v146, v172
	v_mov_b32_e32 v147, v172
	v_mov_b32_e32 v148, v172
	v_mov_b32_e32 v149, v172
	v_mov_b32_e32 v150, v172
	v_mov_b32_e32 v151, v172
	v_mov_b32_e32 v68, v172
	v_mov_b32_e32 v69, v172
	v_mov_b32_e32 v70, v172
	v_mov_b32_e32 v71, v172
	v_mov_b32_e32 v92, v172
	v_mov_b32_e32 v93, v172
	v_mov_b32_e32 v94, v172
	v_mov_b32_e32 v95, v172
	v_mov_b32_e32 v116, v172
	v_mov_b32_e32 v117, v172
	v_mov_b32_e32 v118, v172
	v_mov_b32_e32 v119, v172
	v_mov_b32_e32 v124, v172
	v_mov_b32_e32 v125, v172
	v_mov_b32_e32 v126, v172
	v_mov_b32_e32 v127, v172
	v_mov_b32_e32 v132, v172
	v_mov_b32_e32 v133, v172
	v_mov_b32_e32 v134, v172
	v_mov_b32_e32 v135, v172
	v_mov_b32_e32 v140, v172
	v_mov_b32_e32 v141, v172
	v_mov_b32_e32 v142, v172
	v_mov_b32_e32 v143, v172
	v_mov_b32_e32 v152, v172
	v_mov_b32_e32 v153, v172
	v_mov_b32_e32 v154, v172
	v_mov_b32_e32 v155, v172
	v_mov_b32_e32 v156, v172
	v_mov_b32_e32 v157, v172
	v_mov_b32_e32 v158, v172
	v_mov_b32_e32 v159, v172
	s_branch .Lz1102_mid

.Lz1102_mid:
	s_waitcnt vmcnt(4)
	s_waitcnt lgkmcnt(0)
	s_setprio 1
	s_barrier
	v_mfma_f32_16x16x32_bf16 v[156:159], v[72:75], v[176:179], v[156:159]
	v_mfma_f32_16x16x32_bf16 v[152:155], v[80:83], v[176:179], v[152:155]
	v_mfma_f32_16x16x32_bf16 v[140:143], v[72:75], v[184:187], v[140:143]
	v_mfma_f32_16x16x32_bf16 v[132:135], v[80:83], v[184:187], v[132:135]
	v_mfma_f32_16x16x32_bf16 v[124:127], v[72:75], v[192:195], v[124:127]
	v_mfma_f32_16x16x32_bf16 v[116:119], v[80:83], v[192:195], v[116:119]
	v_mfma_f32_16x16x32_bf16 v[92:95], v[72:75], v[202:205], v[92:95]
	v_mfma_f32_16x16x32_bf16 v[68:71], v[80:83], v[202:205], v[68:71]
	v_mfma_f32_16x16x32_bf16 v[156:159], v[76:79], v[180:183], v[156:159]
	v_mfma_f32_16x16x32_bf16 v[152:155], v[84:87], v[180:183], v[152:155]
	v_mfma_f32_16x16x32_bf16 v[140:143], v[76:79], v[188:191], v[140:143]
	v_mfma_f32_16x16x32_bf16 v[132:135], v[84:87], v[188:191], v[132:135]
	v_mfma_f32_16x16x32_bf16 v[124:127], v[76:79], v[196:199], v[124:127]
	v_mfma_f32_16x16x32_bf16 v[116:119], v[84:87], v[196:199], v[116:119]
	v_mfma_f32_16x16x32_bf16 v[92:95], v[76:79], v[206:209], v[92:95]
	v_mfma_f32_16x16x32_bf16 v[68:71], v[84:87], v[206:209], v[68:71]
	s_setprio 0
	s_setprio 1
	v_mfma_f32_16x16x32_bf16 v[148:151], v[96:99], v[176:179], v[148:151]
	v_mfma_f32_16x16x32_bf16 v[144:147], v[104:107], v[176:179], v[144:147]
	v_mfma_f32_16x16x32_bf16 v[136:139], v[96:99], v[184:187], v[136:139]
	v_mfma_f32_16x16x32_bf16 v[128:131], v[104:107], v[184:187], v[128:131]
	v_mfma_f32_16x16x32_bf16 v[120:123], v[96:99], v[192:195], v[120:123]
	v_mfma_f32_16x16x32_bf16 v[112:115], v[104:107], v[192:195], v[112:115]
	v_mfma_f32_16x16x32_bf16 v[88:91], v[96:99], v[202:205], v[88:91]
	v_mfma_f32_16x16x32_bf16 v[64:67], v[104:107], v[202:205], v[64:67]
	v_mfma_f32_16x16x32_bf16 v[148:151], v[100:103], v[180:183], v[148:151]
	v_mfma_f32_16x16x32_bf16 v[144:147], v[108:111], v[180:183], v[144:147]
	v_mfma_f32_16x16x32_bf16 v[136:139], v[100:103], v[188:191], v[136:139]
	v_mfma_f32_16x16x32_bf16 v[128:131], v[108:111], v[188:191], v[128:131]
	v_mfma_f32_16x16x32_bf16 v[120:123], v[100:103], v[196:199], v[120:123]
	v_mfma_f32_16x16x32_bf16 v[112:115], v[108:111], v[196:199], v[112:115]
	v_mfma_f32_16x16x32_bf16 v[88:91], v[100:103], v[206:209], v[88:91]
	v_mfma_f32_16x16x32_bf16 v[64:67], v[108:111], v[206:209], v[64:67]
	s_barrier
	s_setprio 0
	s_add_i32 s68, s68, s53
	v_lshl_add_u64 v[170:171], s[34:35], 0, v[200:201]
	s_mov_b32 m0, s68
	ds_read_b128 v[176:179], v174 offset:16384
	ds_read_b128 v[180:183], v174 offset:17408
	ds_read_b128 v[184:187], v174 offset:18432
	ds_read_b128 v[188:191], v174 offset:19456
	ds_read_b128 v[192:195], v174 offset:20480
	ds_read_b128 v[196:199], v174 offset:21504
	ds_read_b128 v[202:205], v174 offset:22528
	ds_read_b128 v[206:209], v174 offset:23552
	global_load_lds_dwordx4 v[170:171], off
	s_add_i32 m0, s68, 0x2000
	s_add_u32 s68, s34, 0x80000
	v_lshl_add_u64 v[212:213], s[34:35], 0, v[160:161]
	s_addc_u32 s69, s35, 0
	s_add_i32 s70, s70, s53
	global_load_lds_dwordx4 v[212:213], off
	v_lshl_add_u64 v[214:215], s[68:69], 0, v[200:201]
	s_mov_b32 m0, s70
	global_load_lds_dwordx4 v[214:215], off
	v_lshl_add_u64 v[214:215], s[68:69], 0, v[160:161]
	s_add_i32 m0, s70, 0x2000
	s_nop 0
	global_load_lds_dwordx4 v[214:215], off
	s_waitcnt vmcnt(4)
	s_waitcnt lgkmcnt(0)
	s_setprio 1
	s_barrier
	v_mfma_f32_16x16x32_bf16 v[60:63], v[72:75], v[176:179], v[60:63]
	v_mfma_f32_16x16x32_bf16 v[52:55], v[80:83], v[176:179], v[52:55]
	v_mfma_f32_16x16x32_bf16 v[44:47], v[72:75], v[184:187], v[44:47]
	v_mfma_f32_16x16x32_bf16 v[36:39], v[80:83], v[184:187], v[36:39]
	v_mfma_f32_16x16x32_bf16 v[28:31], v[72:75], v[192:195], v[28:31]
	v_mfma_f32_16x16x32_bf16 v[20:23], v[80:83], v[192:195], v[20:23]
	v_mfma_f32_16x16x32_bf16 v[12:15], v[72:75], v[202:205], v[12:15]
	v_mfma_f32_16x16x32_bf16 v[4:7], v[80:83], v[202:205], v[4:7]
	v_mfma_f32_16x16x32_bf16 v[60:63], v[76:79], v[180:183], v[60:63]
	v_mfma_f32_16x16x32_bf16 v[52:55], v[84:87], v[180:183], v[52:55]
	v_mfma_f32_16x16x32_bf16 v[44:47], v[76:79], v[188:191], v[44:47]
	v_mfma_f32_16x16x32_bf16 v[36:39], v[84:87], v[188:191], v[36:39]
	v_mfma_f32_16x16x32_bf16 v[28:31], v[76:79], v[196:199], v[28:31]
	v_mfma_f32_16x16x32_bf16 v[20:23], v[84:87], v[196:199], v[20:23]
	v_mfma_f32_16x16x32_bf16 v[12:15], v[76:79], v[206:209], v[12:15]
	v_mfma_f32_16x16x32_bf16 v[4:7], v[84:87], v[206:209], v[4:7]
	s_setprio 0
	s_setprio 1
	v_mfma_f32_16x16x32_bf16 v[56:59], v[96:99], v[176:179], v[56:59]
	v_mfma_f32_16x16x32_bf16 v[48:51], v[104:107], v[176:179], v[48:51]
	v_mfma_f32_16x16x32_bf16 v[40:43], v[96:99], v[184:187], v[40:43]
	v_mfma_f32_16x16x32_bf16 v[32:35], v[104:107], v[184:187], v[32:35]
	v_mfma_f32_16x16x32_bf16 v[24:27], v[96:99], v[192:195], v[24:27]
	v_mfma_f32_16x16x32_bf16 v[16:19], v[104:107], v[192:195], v[16:19]
	v_mfma_f32_16x16x32_bf16 v[8:11], v[96:99], v[202:205], v[8:11]
	v_mfma_f32_16x16x32_bf16 v[0:3], v[104:107], v[202:205], v[0:3]
	v_mfma_f32_16x16x32_bf16 v[56:59], v[100:103], v[180:183], v[56:59]
	v_mfma_f32_16x16x32_bf16 v[48:51], v[108:111], v[180:183], v[48:51]
	v_mfma_f32_16x16x32_bf16 v[40:43], v[100:103], v[188:191], v[40:43]
	v_mfma_f32_16x16x32_bf16 v[32:35], v[108:111], v[188:191], v[32:35]
	v_mfma_f32_16x16x32_bf16 v[24:27], v[100:103], v[196:199], v[24:27]
	v_mfma_f32_16x16x32_bf16 v[16:19], v[108:111], v[196:199], v[16:19]
	v_mfma_f32_16x16x32_bf16 v[8:11], v[100:103], v[206:209], v[8:11]
	v_mfma_f32_16x16x32_bf16 v[0:3], v[108:111], v[206:209], v[0:3]
	s_barrier
	s_setprio 0
	s_add_i32 s68, 0, 0x18000
	s_add_i32 s69, 0, 0x1c000
	v_add_u32_e32 v84, s68, v173
	v_add_u32_e32 v108, s69, v173
	ds_read_b128 v[72:75], v84
	ds_read_b128 v[76:79], v84 offset:1024
	ds_read_b128 v[80:83], v84 offset:2048
	ds_read_b128 v[84:87], v84 offset:3072
	ds_read_b128 v[96:99], v108
	ds_read_b128 v[100:103], v108 offset:1024
	ds_read_b128 v[104:107], v108 offset:2048
	ds_read_b128 v[108:111], v108 offset:3072
	s_mov_b32 m0, s31
	s_nop 0
	global_load_lds_dwordx4 v164, s[36:37]
	s_mov_b32 m0, s42
	s_nop 0
	global_load_lds_dwordx4 v162, s[36:37]
	s_add_u32 s36, s36, 0x80000
	s_addc_u32 s37, s37, 0
	s_mov_b32 m0, s43
	v_lshl_add_u64 v[218:219], s[36:37], 0, v[164:165]
	ds_read_b128 v[176:179], v174 offset:32768
	ds_read_b128 v[180:183], v174 offset:33792
	ds_read_b128 v[184:187], v174 offset:34816
	ds_read_b128 v[188:191], v174 offset:35840
	ds_read_b128 v[192:195], v174 offset:36864
	ds_read_b128 v[196:199], v174 offset:37888
	ds_read_b128 v[202:205], v174 offset:38912
	ds_read_b128 v[206:209], v174 offset:39936
	global_load_lds_dwordx4 v[218:219], off
	v_lshl_add_u64 v[218:219], s[36:37], 0, v[162:163]
	s_mov_b32 m0, s54
	s_nop 0
	global_load_lds_dwordx4 v[218:219], off
	s_waitcnt vmcnt(4)
	s_waitcnt lgkmcnt(0)
	s_setprio 1
	s_barrier
	v_mfma_f32_16x16x32_bf16 v[156:159], v[72:75], v[176:179], v[156:159]
	v_mfma_f32_16x16x32_bf16 v[152:155], v[80:83], v[176:179], v[152:155]
	v_mfma_f32_16x16x32_bf16 v[140:143], v[72:75], v[184:187], v[140:143]
	v_mfma_f32_16x16x32_bf16 v[132:135], v[80:83], v[184:187], v[132:135]
	v_mfma_f32_16x16x32_bf16 v[124:127], v[72:75], v[192:195], v[124:127]
	v_mfma_f32_16x16x32_bf16 v[116:119], v[80:83], v[192:195], v[116:119]
	v_mfma_f32_16x16x32_bf16 v[92:95], v[72:75], v[202:205], v[92:95]
	v_mfma_f32_16x16x32_bf16 v[68:71], v[80:83], v[202:205], v[68:71]
	v_mfma_f32_16x16x32_bf16 v[156:159], v[76:79], v[180:183], v[156:159]
	v_mfma_f32_16x16x32_bf16 v[152:155], v[84:87], v[180:183], v[152:155]
	v_mfma_f32_16x16x32_bf16 v[140:143], v[76:79], v[188:191], v[140:143]
	v_mfma_f32_16x16x32_bf16 v[132:135], v[84:87], v[188:191], v[132:135]
	v_mfma_f32_16x16x32_bf16 v[124:127], v[76:79], v[196:199], v[124:127]
	v_mfma_f32_16x16x32_bf16 v[116:119], v[84:87], v[196:199], v[116:119]
	v_mfma_f32_16x16x32_bf16 v[92:95], v[76:79], v[206:209], v[92:95]
	v_mfma_f32_16x16x32_bf16 v[68:71], v[84:87], v[206:209], v[68:71]
	s_setprio 0
	s_setprio 1
	v_mfma_f32_16x16x32_bf16 v[148:151], v[96:99], v[176:179], v[148:151]
	v_mfma_f32_16x16x32_bf16 v[144:147], v[104:107], v[176:179], v[144:147]
	v_mfma_f32_16x16x32_bf16 v[136:139], v[96:99], v[184:187], v[136:139]
	v_mfma_f32_16x16x32_bf16 v[128:131], v[104:107], v[184:187], v[128:131]
	v_mfma_f32_16x16x32_bf16 v[120:123], v[96:99], v[192:195], v[120:123]
	v_mfma_f32_16x16x32_bf16 v[112:115], v[104:107], v[192:195], v[112:115]
	v_mfma_f32_16x16x32_bf16 v[88:91], v[96:99], v[202:205], v[88:91]
	v_mfma_f32_16x16x32_bf16 v[64:67], v[104:107], v[202:205], v[64:67]
	v_mfma_f32_16x16x32_bf16 v[148:151], v[100:103], v[180:183], v[148:151]
	v_mfma_f32_16x16x32_bf16 v[144:147], v[108:111], v[180:183], v[144:147]
	v_mfma_f32_16x16x32_bf16 v[136:139], v[100:103], v[188:191], v[136:139]
	v_mfma_f32_16x16x32_bf16 v[128:131], v[108:111], v[188:191], v[128:131]
	v_mfma_f32_16x16x32_bf16 v[120:123], v[100:103], v[196:199], v[120:123]
	v_mfma_f32_16x16x32_bf16 v[112:115], v[108:111], v[196:199], v[112:115]
	v_mfma_f32_16x16x32_bf16 v[88:91], v[100:103], v[206:209], v[88:91]
	v_mfma_f32_16x16x32_bf16 v[64:67], v[108:111], v[206:209], v[64:67]
	s_barrier
	s_setprio 0
	s_add_i32 s36, s68, s53
	v_lshl_add_u64 v[170:171], v[170:171], 0, s[64:65]
	s_mov_b32 m0, s36
	ds_read_b128 v[176:179], v174 offset:49152
	ds_read_b128 v[180:183], v174 offset:50176
	ds_read_b128 v[184:187], v174 offset:51200
	ds_read_b128 v[188:191], v174 offset:52224
	ds_read_b128 v[192:195], v174 offset:53248
	ds_read_b128 v[196:199], v174 offset:54272
	ds_read_b128 v[202:205], v174 offset:55296
	ds_read_b128 v[206:209], v174 offset:56320
	global_load_lds_dwordx4 v[170:171], off
	s_add_i32 m0, s36, 0x2000
	s_add_u32 s34, s34, 0x80080
	v_lshl_add_u64 v[170:171], v[212:213], 0, s[64:65]
	s_addc_u32 s35, s35, 0
	s_add_i32 s36, s69, s53
	global_load_lds_dwordx4 v[170:171], off
	v_lshl_add_u64 v[170:171], s[34:35], 0, v[200:201]
	s_mov_b32 m0, s36
	s_nop 0
	global_load_lds_dwordx4 v[170:171], off
	v_lshl_add_u64 v[170:171], s[34:35], 0, v[160:161]
	s_add_i32 m0, s36, 0x2000
	s_nop 0
	global_load_lds_dwordx4 v[170:171], off
	s_waitcnt vmcnt(4)
	s_waitcnt lgkmcnt(0)
	s_setprio 1
	s_barrier
	v_mfma_f32_16x16x32_bf16 v[60:63], v[72:75], v[176:179], v[60:63]
	v_mfma_f32_16x16x32_bf16 v[52:55], v[80:83], v[176:179], v[52:55]
	v_mfma_f32_16x16x32_bf16 v[44:47], v[72:75], v[184:187], v[44:47]
	v_mfma_f32_16x16x32_bf16 v[36:39], v[80:83], v[184:187], v[36:39]
	v_mfma_f32_16x16x32_bf16 v[28:31], v[72:75], v[192:195], v[28:31]
	v_mfma_f32_16x16x32_bf16 v[20:23], v[80:83], v[192:195], v[20:23]
	v_mfma_f32_16x16x32_bf16 v[12:15], v[72:75], v[202:205], v[12:15]
	v_mfma_f32_16x16x32_bf16 v[4:7], v[80:83], v[202:205], v[4:7]
	v_mfma_f32_16x16x32_bf16 v[60:63], v[76:79], v[180:183], v[60:63]
	v_mfma_f32_16x16x32_bf16 v[52:55], v[84:87], v[180:183], v[52:55]
	v_mfma_f32_16x16x32_bf16 v[44:47], v[76:79], v[188:191], v[44:47]
	v_mfma_f32_16x16x32_bf16 v[36:39], v[84:87], v[188:191], v[36:39]
	v_mfma_f32_16x16x32_bf16 v[28:31], v[76:79], v[196:199], v[28:31]
	v_mfma_f32_16x16x32_bf16 v[20:23], v[84:87], v[196:199], v[20:23]
	v_mfma_f32_16x16x32_bf16 v[12:15], v[76:79], v[206:209], v[12:15]
	v_mfma_f32_16x16x32_bf16 v[4:7], v[84:87], v[206:209], v[4:7]
	s_setprio 0
	s_setprio 1
	v_mfma_f32_16x16x32_bf16 v[56:59], v[96:99], v[176:179], v[56:59]
	v_mfma_f32_16x16x32_bf16 v[48:51], v[104:107], v[176:179], v[48:51]
	v_mfma_f32_16x16x32_bf16 v[40:43], v[96:99], v[184:187], v[40:43]
	v_mfma_f32_16x16x32_bf16 v[32:35], v[104:107], v[184:187], v[32:35]
	v_mfma_f32_16x16x32_bf16 v[24:27], v[96:99], v[192:195], v[24:27]
	v_mfma_f32_16x16x32_bf16 v[16:19], v[104:107], v[192:195], v[16:19]
	v_mfma_f32_16x16x32_bf16 v[8:11], v[96:99], v[202:205], v[8:11]
	v_mfma_f32_16x16x32_bf16 v[0:3], v[104:107], v[202:205], v[0:3]
	v_mfma_f32_16x16x32_bf16 v[56:59], v[100:103], v[180:183], v[56:59]
	v_mfma_f32_16x16x32_bf16 v[48:51], v[108:111], v[180:183], v[48:51]
	v_mfma_f32_16x16x32_bf16 v[40:43], v[100:103], v[188:191], v[40:43]
	v_mfma_f32_16x16x32_bf16 v[32:35], v[108:111], v[188:191], v[32:35]
	v_mfma_f32_16x16x32_bf16 v[24:27], v[100:103], v[196:199], v[24:27]
	v_mfma_f32_16x16x32_bf16 v[16:19], v[108:111], v[196:199], v[16:19]
	v_mfma_f32_16x16x32_bf16 v[8:11], v[100:103], v[206:209], v[8:11]
	v_mfma_f32_16x16x32_bf16 v[0:3], v[108:111], v[206:209], v[0:3]
	s_barrier
	s_setprio 0
	s_add_i32 s67, s67, 2
	s_add_u32 s4, s4, 0x100
	s_addc_u32 s5, s5, 0
	s_add_u32 s63, s63, 0x100
	s_addc_u32 s66, s66, 0
	s_cmp_gt_u32 s67, 29
	s_cbranch_scc0 .LBB0_1102
	s_and_b64 vcc, exec, s[20:21]
	s_cbranch_vccz .LBB0_1105
	s_barrier

.LBB0_1147:
	s_andn2_b64 vcc, exec, s[14:15]
	v_mov_b32_e32 v127, v138
	v_mov_b32_e32 v126, v138
	v_mov_b32_e32 v125, v138
	v_mov_b32_e32 v124, v138
	v_mov_b32_e32 v123, v138
	v_mov_b32_e32 v122, v138
	v_mov_b32_e32 v121, v138
	v_mov_b32_e32 v120, v138
	v_mov_b32_e32 v111, v138
	v_mov_b32_e32 v110, v138
	v_mov_b32_e32 v109, v138
	v_mov_b32_e32 v108, v138
	v_mov_b32_e32 v107, v138
	v_mov_b32_e32 v106, v138
	v_mov_b32_e32 v105, v138
	v_mov_b32_e32 v104, v138
	v_mov_b32_e32 v95, v138
	v_mov_b32_e32 v94, v138
	v_mov_b32_e32 v93, v138
	v_mov_b32_e32 v92, v138
	v_mov_b32_e32 v91, v138
	v_mov_b32_e32 v90, v138
	v_mov_b32_e32 v89, v138
	v_mov_b32_e32 v88, v138
	v_mov_b32_e32 v79, v138
	v_mov_b32_e32 v78, v138
	v_mov_b32_e32 v77, v138
	v_mov_b32_e32 v76, v138
	v_mov_b32_e32 v75, v138
	v_mov_b32_e32 v74, v138
	v_mov_b32_e32 v73, v138
	v_mov_b32_e32 v72, v138
	v_mov_b32_e32 v119, v138
	v_mov_b32_e32 v118, v138
	v_mov_b32_e32 v117, v138
	v_mov_b32_e32 v116, v138
	v_mov_b32_e32 v115, v138
	v_mov_b32_e32 v114, v138
	v_mov_b32_e32 v113, v138
	v_mov_b32_e32 v112, v138
	v_mov_b32_e32 v103, v138
	v_mov_b32_e32 v102, v138
	v_mov_b32_e32 v101, v138
	v_mov_b32_e32 v100, v138
	v_mov_b32_e32 v99, v138
	v_mov_b32_e32 v98, v138
	v_mov_b32_e32 v97, v138
	v_mov_b32_e32 v96, v138
	v_mov_b32_e32 v87, v138
	v_mov_b32_e32 v86, v138
	v_mov_b32_e32 v85, v138
	v_mov_b32_e32 v84, v138
	v_mov_b32_e32 v83, v138
	v_mov_b32_e32 v82, v138
	v_mov_b32_e32 v81, v138
	v_mov_b32_e32 v80, v138
	v_mov_b32_e32 v71, v138
	v_mov_b32_e32 v70, v138
	v_mov_b32_e32 v69, v138
	v_mov_b32_e32 v68, v138
	v_mov_b32_e32 v67, v138
	v_mov_b32_e32 v66, v138
	v_mov_b32_e32 v65, v138
	v_mov_b32_e32 v64, v138
	v_mov_b32_e32 v63, v138
	v_mov_b32_e32 v62, v138
	v_mov_b32_e32 v61, v138
	v_mov_b32_e32 v60, v138
	v_mov_b32_e32 v59, v138
	v_mov_b32_e32 v58, v138
	v_mov_b32_e32 v57, v138
	v_mov_b32_e32 v56, v138
	v_mov_b32_e32 v47, v138
	v_mov_b32_e32 v46, v138
	v_mov_b32_e32 v45, v138
	v_mov_b32_e32 v44, v138
	v_mov_b32_e32 v43, v138
	v_mov_b32_e32 v42, v138
	v_mov_b32_e32 v41, v138
	v_mov_b32_e32 v40, v138
	v_mov_b32_e32 v31, v138
	v_mov_b32_e32 v30, v138
	v_mov_b32_e32 v29, v138
	v_mov_b32_e32 v28, v138
	v_mov_b32_e32 v27, v138
	v_mov_b32_e32 v26, v138
	v_mov_b32_e32 v25, v138
	v_mov_b32_e32 v24, v138
	v_mov_b32_e32 v15, v138
	v_mov_b32_e32 v14, v138
	v_mov_b32_e32 v13, v138
	v_mov_b32_e32 v12, v138
	v_mov_b32_e32 v11, v138
	v_mov_b32_e32 v10, v138
	v_mov_b32_e32 v9, v138
	v_mov_b32_e32 v8, v138
	v_mov_b32_e32 v55, v138
	v_mov_b32_e32 v54, v138
	v_mov_b32_e32 v53, v138
	v_mov_b32_e32 v52, v138
	v_mov_b32_e32 v51, v138
	v_mov_b32_e32 v50, v138
	v_mov_b32_e32 v49, v138
	v_mov_b32_e32 v48, v138
	v_mov_b32_e32 v39, v138
	v_mov_b32_e32 v38, v138
	v_mov_b32_e32 v37, v138
	v_mov_b32_e32 v36, v138
	v_mov_b32_e32 v35, v138
	v_mov_b32_e32 v34, v138
	v_mov_b32_e32 v33, v138
	v_mov_b32_e32 v32, v138
	v_mov_b32_e32 v23, v138
	v_mov_b32_e32 v22, v138
	v_mov_b32_e32 v21, v138
	v_mov_b32_e32 v20, v138
	v_mov_b32_e32 v19, v138
	v_mov_b32_e32 v18, v138
	v_mov_b32_e32 v17, v138
	v_mov_b32_e32 v16, v138
	v_mov_b32_e32 v7, v138
	v_mov_b32_e32 v6, v138
	v_mov_b32_e32 v5, v138
	v_mov_b32_e32 v4, v138
	v_mov_b32_e32 v3, v138
	v_mov_b32_e32 v2, v138
	v_mov_b32_e32 v1, v138
	v_mov_b32_e32 v0, v138
	s_cbranch_vccnz .LBB0_1151
	s_add_u32 s20, s20, 0x80
	s_addc_u32 s21, s21, 0
	s_add_u32 s49, s22, 0x100
	s_addc_u32 s50, s23, 0
	s_mov_b32 s22, 0
	s_add_i32 s51, s22, 2
	s_add_u32 s53, s20, 0x80
	s_addc_u32 s23, s21, 0
	s_add_i32 s56, 0, 0x10000
	s_cmp_eq_u32 s40, s22
	s_cselect_b32 s23, s5, s23
	s_cselect_b32 s22, s4, s53
	v_add_u32_e32 v141, s56, v139
	s_cselect_b32 s55, s19, s50
	s_cselect_b32 s54, s18, s49
	s_add_i32 s53, 0, 0x14000
	ds_read_b128 v[142:145], v141
	ds_read_b128 v[146:149], v141 offset:1024
	ds_read_b128 v[150:153], v141 offset:2048
	ds_read_b128 v[154:157], v141 offset:3072
	v_add_u32_e32 v141, s53, v139
	ds_read_b128 v[158:161], v141
	ds_read_b128 v[162:165], v141 offset:1024
	ds_read_b128 v[166:169], v141 offset:2048
	ds_read_b128 v[170:173], v141 offset:3072
	v_lshl_add_u64 v[198:199], s[20:21], 0, v[134:135]
	s_add_i32 m0, s29, 0xc000
	ds_read_b128 v[174:177], v140
	ds_read_b128 v[178:181], v140 offset:1024
	ds_read_b128 v[182:185], v140 offset:2048
	ds_read_b128 v[186:189], v140 offset:3072
	ds_read_b128 v[190:193], v140 offset:4096
	ds_read_b128 v[194:197], v140 offset:5120
	ds_read_b128 v[202:205], v140 offset:6144
	ds_read_b128 v[206:209], v140 offset:7168
	global_load_lds_dwordx4 v[198:199], off
	v_lshl_add_u64 v[198:199], s[20:21], 0, v[136:137]
	s_add_i32 m0, s29, 0xe000
	s_nop 0
	global_load_lds_dwordx4 v[198:199], off
	v_mov_b32_e32 v0, v138
	v_mov_b32_e32 v1, v138
	v_mov_b32_e32 v2, v138
	v_mov_b32_e32 v3, v138
	v_mov_b32_e32 v4, v138
	v_mov_b32_e32 v5, v138
	v_mov_b32_e32 v6, v138
	v_mov_b32_e32 v7, v138
	v_mov_b32_e32 v16, v138
	v_mov_b32_e32 v17, v138
	v_mov_b32_e32 v18, v138
	v_mov_b32_e32 v19, v138
	v_mov_b32_e32 v20, v138
	v_mov_b32_e32 v21, v138
	v_mov_b32_e32 v22, v138
	v_mov_b32_e32 v23, v138
	v_mov_b32_e32 v32, v138
	v_mov_b32_e32 v33, v138
	v_mov_b32_e32 v34, v138
	v_mov_b32_e32 v35, v138
	v_mov_b32_e32 v36, v138
	v_mov_b32_e32 v37, v138
	v_mov_b32_e32 v38, v138
	v_mov_b32_e32 v39, v138
	v_mov_b32_e32 v48, v138
	v_mov_b32_e32 v49, v138
	v_mov_b32_e32 v50, v138
	v_mov_b32_e32 v51, v138
	v_mov_b32_e32 v52, v138
	v_mov_b32_e32 v53, v138
	v_mov_b32_e32 v54, v138
	v_mov_b32_e32 v55, v138
	v_mov_b32_e32 v8, v138
	v_mov_b32_e32 v9, v138
	v_mov_b32_e32 v10, v138
	v_mov_b32_e32 v11, v138
	v_mov_b32_e32 v12, v138
	v_mov_b32_e32 v13, v138
	v_mov_b32_e32 v14, v138
	v_mov_b32_e32 v15, v138
	v_mov_b32_e32 v24, v138
	v_mov_b32_e32 v25, v138
	v_mov_b32_e32 v26, v138
	v_mov_b32_e32 v27, v138
	v_mov_b32_e32 v28, v138
	v_mov_b32_e32 v29, v138
	v_mov_b32_e32 v30, v138
	v_mov_b32_e32 v31, v138
	v_mov_b32_e32 v40, v138
	v_mov_b32_e32 v41, v138
	v_mov_b32_e32 v42, v138
	v_mov_b32_e32 v43, v138
	v_mov_b32_e32 v44, v138
	v_mov_b32_e32 v45, v138
	v_mov_b32_e32 v46, v138
	v_mov_b32_e32 v47, v138
	v_mov_b32_e32 v56, v138
	v_mov_b32_e32 v57, v138
	v_mov_b32_e32 v58, v138
	v_mov_b32_e32 v59, v138
	v_mov_b32_e32 v60, v138
	v_mov_b32_e32 v61, v138
	v_mov_b32_e32 v62, v138
	v_mov_b32_e32 v63, v138
	v_mov_b32_e32 v64, v138
	v_mov_b32_e32 v65, v138
	v_mov_b32_e32 v66, v138
	v_mov_b32_e32 v67, v138
	v_mov_b32_e32 v68, v138
	v_mov_b32_e32 v69, v138
	v_mov_b32_e32 v70, v138
	v_mov_b32_e32 v71, v138
	v_mov_b32_e32 v80, v138
	v_mov_b32_e32 v81, v138
	v_mov_b32_e32 v82, v138
	v_mov_b32_e32 v83, v138
	v_mov_b32_e32 v84, v138
	v_mov_b32_e32 v85, v138
	v_mov_b32_e32 v86, v138
	v_mov_b32_e32 v87, v138
	v_mov_b32_e32 v96, v138
	v_mov_b32_e32 v97, v138
	v_mov_b32_e32 v98, v138
	v_mov_b32_e32 v99, v138
	v_mov_b32_e32 v100, v138
	v_mov_b32_e32 v101, v138
	v_mov_b32_e32 v102, v138
	v_mov_b32_e32 v103, v138
	v_mov_b32_e32 v112, v138
	v_mov_b32_e32 v113, v138
	v_mov_b32_e32 v114, v138
	v_mov_b32_e32 v115, v138
	v_mov_b32_e32 v116, v138
	v_mov_b32_e32 v117, v138
	v_mov_b32_e32 v118, v138
	v_mov_b32_e32 v119, v138
	v_mov_b32_e32 v72, v138
	v_mov_b32_e32 v73, v138
	v_mov_b32_e32 v74, v138
	v_mov_b32_e32 v75, v138
	v_mov_b32_e32 v76, v138
	v_mov_b32_e32 v77, v138
	v_mov_b32_e32 v78, v138
	v_mov_b32_e32 v79, v138
	v_mov_b32_e32 v88, v138
	v_mov_b32_e32 v89, v138
	v_mov_b32_e32 v90, v138
	v_mov_b32_e32 v91, v138
	v_mov_b32_e32 v92, v138
	v_mov_b32_e32 v93, v138
	v_mov_b32_e32 v94, v138
	v_mov_b32_e32 v95, v138
	v_mov_b32_e32 v104, v138
	v_mov_b32_e32 v105, v138
	v_mov_b32_e32 v106, v138
	v_mov_b32_e32 v107, v138
	v_mov_b32_e32 v108, v138
	v_mov_b32_e32 v109, v138
	v_mov_b32_e32 v110, v138
	v_mov_b32_e32 v111, v138
	v_mov_b32_e32 v120, v138
	v_mov_b32_e32 v121, v138
	v_mov_b32_e32 v122, v138
	v_mov_b32_e32 v123, v138
	v_mov_b32_e32 v124, v138
	v_mov_b32_e32 v125, v138
	v_mov_b32_e32 v126, v138
	v_mov_b32_e32 v127, v138
	s_branch .Lz1149_mid

.Lz1149_mid:
	s_waitcnt vmcnt(8)
	s_waitcnt lgkmcnt(0)
	s_setprio 1
	s_barrier
	v_mfma_f32_16x16x32_bf16 v[124:127], v[142:145], v[174:177], v[124:127]
	v_mfma_f32_16x16x32_bf16 v[120:123], v[150:153], v[174:177], v[120:123]
	v_mfma_f32_16x16x32_bf16 v[108:111], v[142:145], v[182:185], v[108:111]
	v_mfma_f32_16x16x32_bf16 v[104:107], v[150:153], v[182:185], v[104:107]
	v_mfma_f32_16x16x32_bf16 v[92:95], v[142:145], v[190:193], v[92:95]
	v_mfma_f32_16x16x32_bf16 v[88:91], v[150:153], v[190:193], v[88:91]
	v_mfma_f32_16x16x32_bf16 v[76:79], v[142:145], v[202:205], v[76:79]
	v_mfma_f32_16x16x32_bf16 v[72:75], v[150:153], v[202:205], v[72:75]
	v_mfma_f32_16x16x32_bf16 v[124:127], v[146:149], v[178:181], v[124:127]
	v_mfma_f32_16x16x32_bf16 v[120:123], v[154:157], v[178:181], v[120:123]
	v_mfma_f32_16x16x32_bf16 v[108:111], v[146:149], v[186:189], v[108:111]
	v_mfma_f32_16x16x32_bf16 v[104:107], v[154:157], v[186:189], v[104:107]
	v_mfma_f32_16x16x32_bf16 v[92:95], v[146:149], v[194:197], v[92:95]
	v_mfma_f32_16x16x32_bf16 v[88:91], v[154:157], v[194:197], v[88:91]
	v_mfma_f32_16x16x32_bf16 v[76:79], v[146:149], v[206:209], v[76:79]
	v_mfma_f32_16x16x32_bf16 v[72:75], v[154:157], v[206:209], v[72:75]
	s_setprio 0
	s_setprio 1
	v_mfma_f32_16x16x32_bf16 v[116:119], v[158:161], v[174:177], v[116:119]
	v_mfma_f32_16x16x32_bf16 v[112:115], v[166:169], v[174:177], v[112:115]
	v_mfma_f32_16x16x32_bf16 v[100:103], v[158:161], v[182:185], v[100:103]
	v_mfma_f32_16x16x32_bf16 v[96:99], v[166:169], v[182:185], v[96:99]
	v_mfma_f32_16x16x32_bf16 v[84:87], v[158:161], v[190:193], v[84:87]
	v_mfma_f32_16x16x32_bf16 v[80:83], v[166:169], v[190:193], v[80:83]
	v_mfma_f32_16x16x32_bf16 v[68:71], v[158:161], v[202:205], v[68:71]
	v_mfma_f32_16x16x32_bf16 v[64:67], v[166:169], v[202:205], v[64:67]
	v_mfma_f32_16x16x32_bf16 v[116:119], v[162:165], v[178:181], v[116:119]
	v_mfma_f32_16x16x32_bf16 v[112:115], v[170:173], v[178:181], v[112:115]
	v_mfma_f32_16x16x32_bf16 v[100:103], v[162:165], v[186:189], v[100:103]
	v_mfma_f32_16x16x32_bf16 v[96:99], v[170:173], v[186:189], v[96:99]
	v_mfma_f32_16x16x32_bf16 v[84:87], v[162:165], v[194:197], v[84:87]
	v_mfma_f32_16x16x32_bf16 v[80:83], v[170:173], v[194:197], v[80:83]
	v_mfma_f32_16x16x32_bf16 v[68:71], v[162:165], v[206:209], v[68:71]
	v_mfma_f32_16x16x32_bf16 v[64:67], v[170:173], v[206:209], v[64:67]
	s_barrier
	s_setprio 0
	s_add_i32 s56, s56, s28
	v_lshl_add_u64 v[198:199], s[54:55], 0, v[200:201]
	s_mov_b32 m0, s56
	ds_read_b128 v[174:177], v140 offset:16384
	ds_read_b128 v[178:181], v140 offset:17408
	ds_read_b128 v[182:185], v140 offset:18432
	ds_read_b128 v[186:189], v140 offset:19456
	ds_read_b128 v[190:193], v140 offset:20480
	ds_read_b128 v[194:197], v140 offset:21504
	ds_read_b128 v[202:205], v140 offset:22528
	ds_read_b128 v[206:209], v140 offset:23552
	global_load_lds_dwordx4 v[198:199], off
	s_add_i32 m0, s56, 0x2000
	v_lshl_add_u64 v[212:213], s[54:55], 0, v[128:129]
	s_add_u32 s54, s54, s8
	s_addc_u32 s55, s55, s9
	s_add_i32 s53, s53, s28
	global_load_lds_dwordx4 v[212:213], off
	v_lshl_add_u64 v[214:215], s[54:55], 0, v[200:201]
	s_mov_b32 m0, s53
	v_lshl_add_u64 v[216:217], s[54:55], 0, v[128:129]
	global_load_lds_dwordx4 v[214:215], off
	s_add_i32 m0, s53, 0x2000
	v_lshl_add_u64 v[218:219], s[22:23], 0, v[132:133]
	global_load_lds_dwordx4 v[216:217], off
	s_mov_b32 m0, s29
	v_lshl_add_u64 v[220:221], s[22:23], 0, v[130:131]
	global_load_lds_dwordx4 v[218:219], off
	s_mov_b32 m0, s30
	s_nop 0
	global_load_lds_dwordx4 v[220:221], off
	s_waitcnt vmcnt(8)
	s_waitcnt lgkmcnt(0)
	s_setprio 1
	s_barrier
	v_mfma_f32_16x16x32_bf16 v[60:63], v[142:145], v[174:177], v[60:63]
	v_mfma_f32_16x16x32_bf16 v[56:59], v[150:153], v[174:177], v[56:59]
	v_mfma_f32_16x16x32_bf16 v[44:47], v[142:145], v[182:185], v[44:47]
	v_mfma_f32_16x16x32_bf16 v[40:43], v[150:153], v[182:185], v[40:43]
	v_mfma_f32_16x16x32_bf16 v[28:31], v[142:145], v[190:193], v[28:31]
	v_mfma_f32_16x16x32_bf16 v[24:27], v[150:153], v[190:193], v[24:27]
	v_mfma_f32_16x16x32_bf16 v[12:15], v[142:145], v[202:205], v[12:15]
	v_mfma_f32_16x16x32_bf16 v[8:11], v[150:153], v[202:205], v[8:11]
	v_mfma_f32_16x16x32_bf16 v[60:63], v[146:149], v[178:181], v[60:63]
	v_mfma_f32_16x16x32_bf16 v[56:59], v[154:157], v[178:181], v[56:59]
	v_mfma_f32_16x16x32_bf16 v[44:47], v[146:149], v[186:189], v[44:47]
	v_mfma_f32_16x16x32_bf16 v[40:43], v[154:157], v[186:189], v[40:43]
	v_mfma_f32_16x16x32_bf16 v[28:31], v[146:149], v[194:197], v[28:31]
	v_mfma_f32_16x16x32_bf16 v[24:27], v[154:157], v[194:197], v[24:27]
	v_mfma_f32_16x16x32_bf16 v[12:15], v[146:149], v[206:209], v[12:15]
	v_mfma_f32_16x16x32_bf16 v[8:11], v[154:157], v[206:209], v[8:11]
	s_setprio 0
	s_setprio 1
	v_mfma_f32_16x16x32_bf16 v[52:55], v[158:161], v[174:177], v[52:55]
	v_mfma_f32_16x16x32_bf16 v[48:51], v[166:169], v[174:177], v[48:51]
	v_mfma_f32_16x16x32_bf16 v[36:39], v[158:161], v[182:185], v[36:39]
	v_mfma_f32_16x16x32_bf16 v[32:35], v[166:169], v[182:185], v[32:35]
	v_mfma_f32_16x16x32_bf16 v[20:23], v[158:161], v[190:193], v[20:23]
	v_mfma_f32_16x16x32_bf16 v[16:19], v[166:169], v[190:193], v[16:19]
	v_mfma_f32_16x16x32_bf16 v[4:7], v[158:161], v[202:205], v[4:7]
	v_mfma_f32_16x16x32_bf16 v[0:3], v[166:169], v[202:205], v[0:3]
	v_mfma_f32_16x16x32_bf16 v[52:55], v[162:165], v[178:181], v[52:55]
	v_mfma_f32_16x16x32_bf16 v[48:51], v[170:173], v[178:181], v[48:51]
	v_mfma_f32_16x16x32_bf16 v[36:39], v[162:165], v[186:189], v[36:39]
	v_mfma_f32_16x16x32_bf16 v[32:35], v[170:173], v[186:189], v[32:35]
	v_mfma_f32_16x16x32_bf16 v[20:23], v[162:165], v[194:197], v[20:23]
	v_mfma_f32_16x16x32_bf16 v[16:19], v[170:173], v[194:197], v[16:19]
	v_mfma_f32_16x16x32_bf16 v[4:7], v[162:165], v[206:209], v[4:7]
	v_mfma_f32_16x16x32_bf16 v[0:3], v[170:173], v[206:209], v[0:3]
	s_barrier
	s_setprio 0
	s_add_i32 s53, 0, 0x18000
	v_add_u32_e32 v141, s53, v139
	s_add_i32 s54, 0, 0x1c000
	ds_read_b128 v[142:145], v141
	ds_read_b128 v[146:149], v141 offset:1024
	ds_read_b128 v[150:153], v141 offset:2048
	ds_read_b128 v[154:157], v141 offset:3072
	v_add_u32_e32 v141, s54, v139
	ds_read_b128 v[158:161], v141
	ds_read_b128 v[162:165], v141 offset:1024
	ds_read_b128 v[166:169], v141 offset:2048
	ds_read_b128 v[170:173], v141 offset:3072
	s_add_u32 s22, s22, s8
	s_addc_u32 s23, s23, s9
	s_mov_b32 m0, s31
	v_lshl_add_u64 v[222:223], s[22:23], 0, v[132:133]
	ds_read_b128 v[174:177], v140 offset:32768
	ds_read_b128 v[178:181], v140 offset:33792
	ds_read_b128 v[182:185], v140 offset:34816
	ds_read_b128 v[186:189], v140 offset:35840
	ds_read_b128 v[190:193], v140 offset:36864
	ds_read_b128 v[194:197], v140 offset:37888
	ds_read_b128 v[202:205], v140 offset:38912
	ds_read_b128 v[206:209], v140 offset:39936
	global_load_lds_dwordx4 v[222:223], off
	v_lshl_add_u64 v[222:223], s[22:23], 0, v[130:131]
	s_mov_b32 m0, s33
	s_nop 0
	global_load_lds_dwordx4 v[222:223], off
	s_waitcnt vmcnt(8)
	s_waitcnt lgkmcnt(0)
	s_setprio 1
	s_barrier
	v_mfma_f32_16x16x32_bf16 v[124:127], v[142:145], v[174:177], v[124:127]
	v_mfma_f32_16x16x32_bf16 v[120:123], v[150:153], v[174:177], v[120:123]
	v_mfma_f32_16x16x32_bf16 v[108:111], v[142:145], v[182:185], v[108:111]
	v_mfma_f32_16x16x32_bf16 v[104:107], v[150:153], v[182:185], v[104:107]
	v_mfma_f32_16x16x32_bf16 v[92:95], v[142:145], v[190:193], v[92:95]
	v_mfma_f32_16x16x32_bf16 v[88:91], v[150:153], v[190:193], v[88:91]
	v_mfma_f32_16x16x32_bf16 v[76:79], v[142:145], v[202:205], v[76:79]
	v_mfma_f32_16x16x32_bf16 v[72:75], v[150:153], v[202:205], v[72:75]
	v_mfma_f32_16x16x32_bf16 v[124:127], v[146:149], v[178:181], v[124:127]
	v_mfma_f32_16x16x32_bf16 v[120:123], v[154:157], v[178:181], v[120:123]
	v_mfma_f32_16x16x32_bf16 v[108:111], v[146:149], v[186:189], v[108:111]
	v_mfma_f32_16x16x32_bf16 v[104:107], v[154:157], v[186:189], v[104:107]
	v_mfma_f32_16x16x32_bf16 v[92:95], v[146:149], v[194:197], v[92:95]
	v_mfma_f32_16x16x32_bf16 v[88:91], v[154:157], v[194:197], v[88:91]
	v_mfma_f32_16x16x32_bf16 v[76:79], v[146:149], v[206:209], v[76:79]
	v_mfma_f32_16x16x32_bf16 v[72:75], v[154:157], v[206:209], v[72:75]
	s_setprio 0
	s_setprio 1
	v_mfma_f32_16x16x32_bf16 v[116:119], v[158:161], v[174:177], v[116:119]
	v_mfma_f32_16x16x32_bf16 v[112:115], v[166:169], v[174:177], v[112:115]
	v_mfma_f32_16x16x32_bf16 v[100:103], v[158:161], v[182:185], v[100:103]
	v_mfma_f32_16x16x32_bf16 v[96:99], v[166:169], v[182:185], v[96:99]
	v_mfma_f32_16x16x32_bf16 v[84:87], v[158:161], v[190:193], v[84:87]
	v_mfma_f32_16x16x32_bf16 v[80:83], v[166:169], v[190:193], v[80:83]
	v_mfma_f32_16x16x32_bf16 v[68:71], v[158:161], v[202:205], v[68:71]
	v_mfma_f32_16x16x32_bf16 v[64:67], v[166:169], v[202:205], v[64:67]
	v_mfma_f32_16x16x32_bf16 v[116:119], v[162:165], v[178:181], v[116:119]
	v_mfma_f32_16x16x32_bf16 v[112:115], v[170:173], v[178:181], v[112:115]
	v_mfma_f32_16x16x32_bf16 v[100:103], v[162:165], v[186:189], v[100:103]
	v_mfma_f32_16x16x32_bf16 v[96:99], v[170:173], v[186:189], v[96:99]
	v_mfma_f32_16x16x32_bf16 v[84:87], v[162:165], v[194:197], v[84:87]
	v_mfma_f32_16x16x32_bf16 v[80:83], v[170:173], v[194:197], v[80:83]
	v_mfma_f32_16x16x32_bf16 v[68:71], v[162:165], v[206:209], v[68:71]
	v_mfma_f32_16x16x32_bf16 v[64:67], v[170:173], v[206:209], v[64:67]
	s_barrier
	s_setprio 0
	s_add_i32 s22, s53, s28
	v_lshl_add_u64 v[198:199], v[198:199], 0, s[64:65]
	s_mov_b32 m0, s22
	ds_read_b128 v[174:177], v140 offset:49152
	ds_read_b128 v[178:181], v140 offset:50176
	ds_read_b128 v[182:185], v140 offset:51200
	ds_read_b128 v[186:189], v140 offset:52224
	ds_read_b128 v[190:193], v140 offset:53248
	ds_read_b128 v[194:197], v140 offset:54272
	ds_read_b128 v[202:205], v140 offset:55296
	ds_read_b128 v[206:209], v140 offset:56320
	global_load_lds_dwordx4 v[198:199], off
	v_lshl_add_u64 v[198:199], v[212:213], 0, s[64:65]
	s_add_i32 m0, s22, 0x2000
	s_add_i32 s22, s54, s28
	global_load_lds_dwordx4 v[198:199], off
	v_lshl_add_u64 v[198:199], v[214:215], 0, s[64:65]
	s_mov_b32 m0, s22
	s_nop 0
	global_load_lds_dwordx4 v[198:199], off
	v_lshl_add_u64 v[198:199], v[216:217], 0, s[64:65]
	s_add_i32 m0, s22, 0x2000
	s_nop 0
	global_load_lds_dwordx4 v[198:199], off
	v_lshl_add_u64 v[198:199], v[218:219], 0, s[64:65]
	s_mov_b32 m0, s36
	s_nop 0
	global_load_lds_dwordx4 v[198:199], off
	v_lshl_add_u64 v[198:199], v[220:221], 0, s[64:65]
	s_mov_b32 m0, s37
	s_nop 0
	global_load_lds_dwordx4 v[198:199], off
	s_waitcnt vmcnt(8)
	s_waitcnt lgkmcnt(0)
	s_setprio 1
	s_barrier
	v_mfma_f32_16x16x32_bf16 v[60:63], v[142:145], v[174:177], v[60:63]
	v_mfma_f32_16x16x32_bf16 v[56:59], v[150:153], v[174:177], v[56:59]
	v_mfma_f32_16x16x32_bf16 v[44:47], v[142:145], v[182:185], v[44:47]
	v_mfma_f32_16x16x32_bf16 v[40:43], v[150:153], v[182:185], v[40:43]
	v_mfma_f32_16x16x32_bf16 v[28:31], v[142:145], v[190:193], v[28:31]
	v_mfma_f32_16x16x32_bf16 v[24:27], v[150:153], v[190:193], v[24:27]
	v_mfma_f32_16x16x32_bf16 v[12:15], v[142:145], v[202:205], v[12:15]
	v_mfma_f32_16x16x32_bf16 v[8:11], v[150:153], v[202:205], v[8:11]
	v_mfma_f32_16x16x32_bf16 v[60:63], v[146:149], v[178:181], v[60:63]
	v_mfma_f32_16x16x32_bf16 v[56:59], v[154:157], v[178:181], v[56:59]
	v_mfma_f32_16x16x32_bf16 v[44:47], v[146:149], v[186:189], v[44:47]
	v_mfma_f32_16x16x32_bf16 v[40:43], v[154:157], v[186:189], v[40:43]
	v_mfma_f32_16x16x32_bf16 v[28:31], v[146:149], v[194:197], v[28:31]
	v_mfma_f32_16x16x32_bf16 v[24:27], v[154:157], v[194:197], v[24:27]
	v_mfma_f32_16x16x32_bf16 v[12:15], v[146:149], v[206:209], v[12:15]
	v_mfma_f32_16x16x32_bf16 v[8:11], v[154:157], v[206:209], v[8:11]
	s_setprio 0
	s_setprio 1
	v_mfma_f32_16x16x32_bf16 v[52:55], v[158:161], v[174:177], v[52:55]
	v_mfma_f32_16x16x32_bf16 v[48:51], v[166:169], v[174:177], v[48:51]
	v_mfma_f32_16x16x32_bf16 v[36:39], v[158:161], v[182:185], v[36:39]
	v_mfma_f32_16x16x32_bf16 v[32:35], v[166:169], v[182:185], v[32:35]
	v_mfma_f32_16x16x32_bf16 v[20:23], v[158:161], v[190:193], v[20:23]
	v_mfma_f32_16x16x32_bf16 v[16:19], v[166:169], v[190:193], v[16:19]
	v_mfma_f32_16x16x32_bf16 v[4:7], v[158:161], v[202:205], v[4:7]
	v_mfma_f32_16x16x32_bf16 v[0:3], v[166:169], v[202:205], v[0:3]
	v_mfma_f32_16x16x32_bf16 v[52:55], v[162:165], v[178:181], v[52:55]
	v_mfma_f32_16x16x32_bf16 v[48:51], v[170:173], v[178:181], v[48:51]
	v_mfma_f32_16x16x32_bf16 v[36:39], v[162:165], v[186:189], v[36:39]
	v_mfma_f32_16x16x32_bf16 v[32:35], v[170:173], v[186:189], v[32:35]
	v_mfma_f32_16x16x32_bf16 v[20:23], v[162:165], v[194:197], v[20:23]
	v_mfma_f32_16x16x32_bf16 v[16:19], v[170:173], v[194:197], v[16:19]
	v_mfma_f32_16x16x32_bf16 v[4:7], v[162:165], v[206:209], v[4:7]
	v_mfma_f32_16x16x32_bf16 v[0:3], v[170:173], v[206:209], v[0:3]
	s_barrier
	s_setprio 0
	s_add_u32 s20, s20, 0x100
	s_addc_u32 s21, s21, 0
	s_add_u32 s49, s49, 0x100
	s_addc_u32 s50, s50, 0
	s_cmp_ge_i32 s51, s34
	s_mov_b32 s22, s51
	s_cbranch_scc0 .LBB0_1149
	s_movk_i32 s53, 0xc000
	s_mov_b64 s[54:55], 0x800

.LBB0_1248:
	s_add_u32 s7, s82, 0x100
	s_addc_u32 s23, s83, 0
	s_mov_b32 s24, -2
	s_waitcnt lgkmcnt(0)
	s_add_u32 s4, s74, 0x100
	s_addc_u32 s5, s75, 0
	s_add_i32 s25, 0, 0x10000
	s_cmpk_eq_i32 s24, 0x54
	s_cselect_b32 vcc_hi, s81, s5
	s_cselect_b32 vcc_lo, s80, s4
	s_cselect_b32 s83, s79, s23
	s_cselect_b32 s82, s78, s7
	s_add_i32 s28, 0, 0x14000
	v_add_u32_e32 v92, s25, v213
	v_add_u32_e32 v124, s28, v213
	ds_read_b128 v[76:79], v92
	ds_read_b128 v[80:83], v92 offset:1024
	ds_read_b128 v[84:87], v92 offset:2048
	ds_read_b128 v[92:95], v92 offset:3072
	ds_read_b128 v[112:115], v124
	ds_read_b128 v[116:119], v124 offset:1024
	ds_read_b128 v[120:123], v124 offset:2048
	ds_read_b128 v[124:127], v124 offset:3072
	v_lshl_add_u64 v[192:193], s[74:75], 0, v[222:223]
	s_add_i32 m0, s85, 0xc000
	ds_read_b128 v[152:155], v206
	ds_read_b128 v[160:163], v206 offset:1024
	ds_read_b128 v[168:171], v206 offset:2048
	ds_read_b128 v[172:175], v206 offset:3072
	ds_read_b128 v[176:179], v206 offset:4096
	ds_read_b128 v[180:183], v206 offset:5120
	ds_read_b128 v[184:187], v206 offset:6144
	ds_read_b128 v[188:191], v206 offset:7168
	global_load_lds_dwordx4 v[192:193], off
	v_lshl_add_u64 v[192:193], s[74:75], 0, v[224:225]
	s_add_i32 m0, s85, 0xe000
	s_nop 0
	global_load_lds_dwordx4 v[192:193], off
	v_mov_b32_e32 v0, v212
	v_mov_b32_e32 v1, v212
	v_mov_b32_e32 v2, v212
	v_mov_b32_e32 v3, v212
	v_mov_b32_e32 v4, v212
	v_mov_b32_e32 v5, v212
	v_mov_b32_e32 v6, v212
	v_mov_b32_e32 v7, v212
	v_mov_b32_e32 v8, v212
	v_mov_b32_e32 v9, v212
	v_mov_b32_e32 v10, v212
	v_mov_b32_e32 v11, v212
	v_mov_b32_e32 v12, v212
	v_mov_b32_e32 v13, v212
	v_mov_b32_e32 v14, v212
	v_mov_b32_e32 v15, v212
	v_mov_b32_e32 v16, v212
	v_mov_b32_e32 v17, v212
	v_mov_b32_e32 v18, v212
	v_mov_b32_e32 v19, v212
	v_mov_b32_e32 v20, v212
	v_mov_b32_e32 v21, v212
	v_mov_b32_e32 v22, v212
	v_mov_b32_e32 v23, v212
	v_mov_b32_e32 v24, v212
	v_mov_b32_e32 v25, v212
	v_mov_b32_e32 v26, v212
	v_mov_b32_e32 v27, v212
	v_mov_b32_e32 v28, v212
	v_mov_b32_e32 v29, v212
	v_mov_b32_e32 v30, v212
	v_mov_b32_e32 v31, v212
	v_mov_b32_e32 v32, v212
	v_mov_b32_e32 v33, v212
	v_mov_b32_e32 v34, v212
	v_mov_b32_e32 v35, v212
	v_mov_b32_e32 v36, v212
	v_mov_b32_e32 v37, v212
	v_mov_b32_e32 v38, v212
	v_mov_b32_e32 v39, v212
	v_mov_b32_e32 v40, v212
	v_mov_b32_e32 v41, v212
	v_mov_b32_e32 v42, v212
	v_mov_b32_e32 v43, v212
	v_mov_b32_e32 v44, v212
	v_mov_b32_e32 v45, v212
	v_mov_b32_e32 v46, v212
	v_mov_b32_e32 v47, v212
	v_mov_b32_e32 v48, v212
	v_mov_b32_e32 v49, v212
	v_mov_b32_e32 v50, v212
	v_mov_b32_e32 v51, v212
	v_mov_b32_e32 v52, v212
	v_mov_b32_e32 v53, v212
	v_mov_b32_e32 v54, v212
	v_mov_b32_e32 v55, v212
	v_mov_b32_e32 v56, v212
	v_mov_b32_e32 v57, v212
	v_mov_b32_e32 v58, v212
	v_mov_b32_e32 v59, v212
	v_mov_b32_e32 v60, v212
	v_mov_b32_e32 v61, v212
	v_mov_b32_e32 v62, v212
	v_mov_b32_e32 v63, v212
	v_mov_b32_e32 v64, v212
	v_mov_b32_e32 v65, v212
	v_mov_b32_e32 v66, v212
	v_mov_b32_e32 v67, v212
	v_mov_b32_e32 v68, v212
	v_mov_b32_e32 v69, v212
	v_mov_b32_e32 v70, v212
	v_mov_b32_e32 v71, v212
	v_mov_b32_e32 v72, v212
	v_mov_b32_e32 v73, v212
	v_mov_b32_e32 v74, v212
	v_mov_b32_e32 v75, v212
	v_mov_b32_e32 v88, v212
	v_mov_b32_e32 v89, v212
	v_mov_b32_e32 v90, v212
	v_mov_b32_e32 v91, v212
	v_mov_b32_e32 v96, v212
	v_mov_b32_e32 v97, v212
	v_mov_b32_e32 v98, v212
	v_mov_b32_e32 v99, v212
	v_mov_b32_e32 v100, v212
	v_mov_b32_e32 v101, v212
	v_mov_b32_e32 v102, v212
	v_mov_b32_e32 v103, v212
	v_mov_b32_e32 v104, v212
	v_mov_b32_e32 v105, v212
	v_mov_b32_e32 v106, v212
	v_mov_b32_e32 v107, v212
	v_mov_b32_e32 v108, v212
	v_mov_b32_e32 v109, v212
	v_mov_b32_e32 v110, v212
	v_mov_b32_e32 v111, v212
	v_mov_b32_e32 v128, v212
	v_mov_b32_e32 v129, v212
	v_mov_b32_e32 v130, v212
	v_mov_b32_e32 v131, v212
	v_mov_b32_e32 v132, v212
	v_mov_b32_e32 v133, v212
	v_mov_b32_e32 v134, v212
	v_mov_b32_e32 v135, v212
	v_mov_b32_e32 v136, v212
	v_mov_b32_e32 v137, v212
	v_mov_b32_e32 v138, v212
	v_mov_b32_e32 v139, v212
	v_mov_b32_e32 v140, v212
	v_mov_b32_e32 v141, v212
	v_mov_b32_e32 v142, v212
	v_mov_b32_e32 v143, v212
	v_mov_b32_e32 v144, v212
	v_mov_b32_e32 v145, v212
	v_mov_b32_e32 v146, v212
	v_mov_b32_e32 v147, v212
	v_mov_b32_e32 v148, v212
	v_mov_b32_e32 v149, v212
	v_mov_b32_e32 v150, v212
	v_mov_b32_e32 v151, v212
	v_mov_b32_e32 v156, v212
	v_mov_b32_e32 v157, v212
	v_mov_b32_e32 v158, v212
	v_mov_b32_e32 v159, v212
	v_mov_b32_e32 v164, v212
	v_mov_b32_e32 v165, v212
	v_mov_b32_e32 v166, v212
	v_mov_b32_e32 v167, v212
	s_branch .Lz1249_mid

.Lz1249_mid:
	s_waitcnt vmcnt(8)
	s_waitcnt lgkmcnt(0)
	s_setprio 1
	s_barrier
	v_mfma_f32_16x16x32_bf16 v[164:167], v[76:79], v[152:155], v[164:167]
	v_mfma_f32_16x16x32_bf16 v[156:159], v[84:87], v[152:155], v[156:159]
	v_mfma_f32_16x16x32_bf16 v[148:151], v[76:79], v[168:171], v[148:151]
	v_mfma_f32_16x16x32_bf16 v[144:147], v[84:87], v[168:171], v[144:147]
	v_mfma_f32_16x16x32_bf16 v[140:143], v[76:79], v[176:179], v[140:143]
	v_mfma_f32_16x16x32_bf16 v[136:139], v[84:87], v[176:179], v[136:139]
	v_mfma_f32_16x16x32_bf16 v[132:135], v[76:79], v[184:187], v[132:135]
	v_mfma_f32_16x16x32_bf16 v[128:131], v[84:87], v[184:187], v[128:131]
	v_mfma_f32_16x16x32_bf16 v[164:167], v[80:83], v[160:163], v[164:167]
	v_mfma_f32_16x16x32_bf16 v[156:159], v[92:95], v[160:163], v[156:159]
	v_mfma_f32_16x16x32_bf16 v[148:151], v[80:83], v[172:175], v[148:151]
	v_mfma_f32_16x16x32_bf16 v[144:147], v[92:95], v[172:175], v[144:147]
	v_mfma_f32_16x16x32_bf16 v[140:143], v[80:83], v[180:183], v[140:143]
	v_mfma_f32_16x16x32_bf16 v[136:139], v[92:95], v[180:183], v[136:139]
	v_mfma_f32_16x16x32_bf16 v[132:135], v[80:83], v[188:191], v[132:135]
	v_mfma_f32_16x16x32_bf16 v[128:131], v[92:95], v[188:191], v[128:131]
	s_setprio 0
	s_setprio 1
	v_mfma_f32_16x16x32_bf16 v[108:111], v[112:115], v[152:155], v[108:111]
	v_mfma_f32_16x16x32_bf16 v[104:107], v[120:123], v[152:155], v[104:107]
	v_mfma_f32_16x16x32_bf16 v[100:103], v[112:115], v[168:171], v[100:103]
	v_mfma_f32_16x16x32_bf16 v[96:99], v[120:123], v[168:171], v[96:99]
	v_mfma_f32_16x16x32_bf16 v[88:91], v[112:115], v[176:179], v[88:91]
	v_mfma_f32_16x16x32_bf16 v[72:75], v[120:123], v[176:179], v[72:75]
	v_mfma_f32_16x16x32_bf16 v[68:71], v[112:115], v[184:187], v[68:71]
	v_mfma_f32_16x16x32_bf16 v[64:67], v[120:123], v[184:187], v[64:67]
	v_mfma_f32_16x16x32_bf16 v[108:111], v[116:119], v[160:163], v[108:111]
	v_mfma_f32_16x16x32_bf16 v[104:107], v[124:127], v[160:163], v[104:107]
	v_mfma_f32_16x16x32_bf16 v[100:103], v[116:119], v[172:175], v[100:103]
	v_mfma_f32_16x16x32_bf16 v[96:99], v[124:127], v[172:175], v[96:99]
	v_mfma_f32_16x16x32_bf16 v[88:91], v[116:119], v[180:183], v[88:91]
	v_mfma_f32_16x16x32_bf16 v[72:75], v[124:127], v[180:183], v[72:75]
	v_mfma_f32_16x16x32_bf16 v[68:71], v[116:119], v[188:191], v[68:71]
	v_mfma_f32_16x16x32_bf16 v[64:67], v[124:127], v[188:191], v[64:67]
	s_barrier
	s_setprio 0
	s_add_i32 s25, s25, s56
	v_lshl_add_u64 v[192:193], s[82:83], 0, v[216:217]
	s_mov_b32 m0, s25
	ds_read_b128 v[152:155], v206 offset:16384
	ds_read_b128 v[160:163], v206 offset:17408
	ds_read_b128 v[168:171], v206 offset:18432
	ds_read_b128 v[172:175], v206 offset:19456
	ds_read_b128 v[176:179], v206 offset:20480
	ds_read_b128 v[180:183], v206 offset:21504
	ds_read_b128 v[184:187], v206 offset:22528
	ds_read_b128 v[188:191], v206 offset:23552
	global_load_lds_dwordx4 v[192:193], off
	s_add_i32 m0, s25, 0x2000
	s_add_u32 s74, s82, 0x160000
	v_lshl_add_u64 v[194:195], s[82:83], 0, v[220:221]
	s_addc_u32 s75, s83, 0
	s_add_i32 s25, s28, s56
	global_load_lds_dwordx4 v[194:195], off
	v_lshl_add_u64 v[196:197], s[74:75], 0, v[216:217]
	s_mov_b32 m0, s25
	v_lshl_add_u64 v[198:199], vcc, 0, v[218:219]
	global_load_lds_dwordx4 v[196:197], off
	v_lshl_add_u64 v[196:197], s[74:75], 0, v[220:221]
	s_add_i32 m0, s25, 0x2000
	s_nop 0
	global_load_lds_dwordx4 v[196:197], off
	v_lshl_add_u64 v[196:197], vcc, 0, v[214:215]
	s_mov_b32 m0, s85
	s_nop 0
	global_load_lds_dwordx4 v[196:197], off
	s_mov_b32 m0, s53
	s_nop 0
	global_load_lds_dwordx4 v[198:199], off
	s_waitcnt vmcnt(8)
	s_waitcnt lgkmcnt(0)
	s_setprio 1
	s_barrier
	v_mfma_f32_16x16x32_bf16 v[60:63], v[76:79], v[152:155], v[60:63]
	v_mfma_f32_16x16x32_bf16 v[56:59], v[84:87], v[152:155], v[56:59]
	v_mfma_f32_16x16x32_bf16 v[52:55], v[76:79], v[168:171], v[52:55]
	v_mfma_f32_16x16x32_bf16 v[48:51], v[84:87], v[168:171], v[48:51]
	v_mfma_f32_16x16x32_bf16 v[44:47], v[76:79], v[176:179], v[44:47]
	v_mfma_f32_16x16x32_bf16 v[40:43], v[84:87], v[176:179], v[40:43]
	v_mfma_f32_16x16x32_bf16 v[36:39], v[76:79], v[184:187], v[36:39]
	v_mfma_f32_16x16x32_bf16 v[32:35], v[84:87], v[184:187], v[32:35]
	v_mfma_f32_16x16x32_bf16 v[60:63], v[80:83], v[160:163], v[60:63]
	v_mfma_f32_16x16x32_bf16 v[56:59], v[92:95], v[160:163], v[56:59]
	v_mfma_f32_16x16x32_bf16 v[52:55], v[80:83], v[172:175], v[52:55]
	v_mfma_f32_16x16x32_bf16 v[48:51], v[92:95], v[172:175], v[48:51]
	v_mfma_f32_16x16x32_bf16 v[44:47], v[80:83], v[180:183], v[44:47]
	v_mfma_f32_16x16x32_bf16 v[40:43], v[92:95], v[180:183], v[40:43]
	v_mfma_f32_16x16x32_bf16 v[36:39], v[80:83], v[188:191], v[36:39]
	v_mfma_f32_16x16x32_bf16 v[32:35], v[92:95], v[188:191], v[32:35]
	s_setprio 0
	s_setprio 1
	v_mfma_f32_16x16x32_bf16 v[28:31], v[112:115], v[152:155], v[28:31]
	v_mfma_f32_16x16x32_bf16 v[24:27], v[120:123], v[152:155], v[24:27]
	v_mfma_f32_16x16x32_bf16 v[20:23], v[112:115], v[168:171], v[20:23]
	v_mfma_f32_16x16x32_bf16 v[16:19], v[120:123], v[168:171], v[16:19]
	v_mfma_f32_16x16x32_bf16 v[12:15], v[112:115], v[176:179], v[12:15]
	v_mfma_f32_16x16x32_bf16 v[8:11], v[120:123], v[176:179], v[8:11]
	v_mfma_f32_16x16x32_bf16 v[4:7], v[112:115], v[184:187], v[4:7]
	v_mfma_f32_16x16x32_bf16 v[0:3], v[120:123], v[184:187], v[0:3]
	v_mfma_f32_16x16x32_bf16 v[28:31], v[116:119], v[160:163], v[28:31]
	v_mfma_f32_16x16x32_bf16 v[24:27], v[124:127], v[160:163], v[24:27]
	v_mfma_f32_16x16x32_bf16 v[20:23], v[116:119], v[172:175], v[20:23]
	v_mfma_f32_16x16x32_bf16 v[16:19], v[124:127], v[172:175], v[16:19]
	v_mfma_f32_16x16x32_bf16 v[12:15], v[116:119], v[180:183], v[12:15]
	v_mfma_f32_16x16x32_bf16 v[8:11], v[124:127], v[180:183], v[8:11]
	v_mfma_f32_16x16x32_bf16 v[4:7], v[116:119], v[188:191], v[4:7]
	v_mfma_f32_16x16x32_bf16 v[0:3], v[124:127], v[188:191], v[0:3]
	s_barrier
	s_setprio 0
	s_add_i32 s25, 0, 0x18000
	s_add_i32 s28, 0, 0x1c000
	v_add_u32_e32 v92, s25, v213
	v_add_u32_e32 v124, s28, v213
	ds_read_b128 v[76:79], v92
	ds_read_b128 v[80:83], v92 offset:1024
	ds_read_b128 v[84:87], v92 offset:2048
	ds_read_b128 v[92:95], v92 offset:3072
	ds_read_b128 v[112:115], v124
	ds_read_b128 v[116:119], v124 offset:1024
	ds_read_b128 v[120:123], v124 offset:2048
	ds_read_b128 v[124:127], v124 offset:3072
	s_add_u32 s74, vcc_lo, 0x160000
	s_addc_u32 s75, vcc_hi, 0
	s_mov_b32 m0, s84
	v_lshl_add_u64 v[202:203], s[74:75], 0, v[214:215]
	ds_read_b128 v[152:155], v206 offset:32768
	ds_read_b128 v[160:163], v206 offset:33792
	ds_read_b128 v[168:171], v206 offset:34816
	ds_read_b128 v[172:175], v206 offset:35840
	ds_read_b128 v[176:179], v206 offset:36864
	ds_read_b128 v[180:183], v206 offset:37888
	ds_read_b128 v[184:187], v206 offset:38912
	ds_read_b128 v[188:191], v206 offset:39936
	global_load_lds_dwordx4 v[202:203], off
	v_lshl_add_u64 v[202:203], s[74:75], 0, v[218:219]
	s_mov_b32 m0, s26
	s_nop 0
	global_load_lds_dwordx4 v[202:203], off
	s_waitcnt vmcnt(8)
	s_waitcnt lgkmcnt(0)
	s_setprio 1
	s_barrier
	v_mfma_f32_16x16x32_bf16 v[164:167], v[76:79], v[152:155], v[164:167]
	v_mfma_f32_16x16x32_bf16 v[156:159], v[84:87], v[152:155], v[156:159]
	v_mfma_f32_16x16x32_bf16 v[148:151], v[76:79], v[168:171], v[148:151]
	v_mfma_f32_16x16x32_bf16 v[144:147], v[84:87], v[168:171], v[144:147]
	v_mfma_f32_16x16x32_bf16 v[140:143], v[76:79], v[176:179], v[140:143]
	v_mfma_f32_16x16x32_bf16 v[136:139], v[84:87], v[176:179], v[136:139]
	v_mfma_f32_16x16x32_bf16 v[132:135], v[76:79], v[184:187], v[132:135]
	v_mfma_f32_16x16x32_bf16 v[128:131], v[84:87], v[184:187], v[128:131]
	v_mfma_f32_16x16x32_bf16 v[164:167], v[80:83], v[160:163], v[164:167]
	v_mfma_f32_16x16x32_bf16 v[156:159], v[92:95], v[160:163], v[156:159]
	v_mfma_f32_16x16x32_bf16 v[148:151], v[80:83], v[172:175], v[148:151]
	v_mfma_f32_16x16x32_bf16 v[144:147], v[92:95], v[172:175], v[144:147]
	v_mfma_f32_16x16x32_bf16 v[140:143], v[80:83], v[180:183], v[140:143]
	v_mfma_f32_16x16x32_bf16 v[136:139], v[92:95], v[180:183], v[136:139]
	v_mfma_f32_16x16x32_bf16 v[132:135], v[80:83], v[188:191], v[132:135]
	v_mfma_f32_16x16x32_bf16 v[128:131], v[92:95], v[188:191], v[128:131]
	s_setprio 0
	s_setprio 1
	v_mfma_f32_16x16x32_bf16 v[108:111], v[112:115], v[152:155], v[108:111]
	v_mfma_f32_16x16x32_bf16 v[104:107], v[120:123], v[152:155], v[104:107]
	v_mfma_f32_16x16x32_bf16 v[100:103], v[112:115], v[168:171], v[100:103]
	v_mfma_f32_16x16x32_bf16 v[96:99], v[120:123], v[168:171], v[96:99]
	v_mfma_f32_16x16x32_bf16 v[88:91], v[112:115], v[176:179], v[88:91]
	v_mfma_f32_16x16x32_bf16 v[72:75], v[120:123], v[176:179], v[72:75]
	v_mfma_f32_16x16x32_bf16 v[68:71], v[112:115], v[184:187], v[68:71]
	v_mfma_f32_16x16x32_bf16 v[64:67], v[120:123], v[184:187], v[64:67]
	v_mfma_f32_16x16x32_bf16 v[108:111], v[116:119], v[160:163], v[108:111]
	v_mfma_f32_16x16x32_bf16 v[104:107], v[124:127], v[160:163], v[104:107]
	v_mfma_f32_16x16x32_bf16 v[100:103], v[116:119], v[172:175], v[100:103]
	v_mfma_f32_16x16x32_bf16 v[96:99], v[124:127], v[172:175], v[96:99]
	v_mfma_f32_16x16x32_bf16 v[88:91], v[116:119], v[180:183], v[88:91]
	v_mfma_f32_16x16x32_bf16 v[72:75], v[124:127], v[180:183], v[72:75]
	v_mfma_f32_16x16x32_bf16 v[68:71], v[116:119], v[188:191], v[68:71]
	v_mfma_f32_16x16x32_bf16 v[64:67], v[124:127], v[188:191], v[64:67]
	s_barrier
	s_setprio 0
	s_add_i32 s25, s25, s56
	v_lshl_add_u64 v[192:193], v[192:193], 0, s[64:65]
	s_mov_b32 m0, s25
	ds_read_b128 v[152:155], v206 offset:49152
	ds_read_b128 v[160:163], v206 offset:50176
	ds_read_b128 v[168:171], v206 offset:51200
	ds_read_b128 v[172:175], v206 offset:52224
	ds_read_b128 v[176:179], v206 offset:53248
	ds_read_b128 v[180:183], v206 offset:54272
	ds_read_b128 v[184:187], v206 offset:55296
	ds_read_b128 v[188:191], v206 offset:56320
	global_load_lds_dwordx4 v[192:193], off
	s_add_i32 m0, s25, 0x2000
	s_add_u32 s74, s82, 0x160080
	v_lshl_add_u64 v[192:193], v[194:195], 0, s[64:65]
	s_addc_u32 s75, s83, 0
	s_add_i32 s25, s28, s56
	global_load_lds_dwordx4 v[192:193], off
	v_lshl_add_u64 v[192:193], s[74:75], 0, v[216:217]
	s_mov_b32 m0, s25
	s_nop 0
	global_load_lds_dwordx4 v[192:193], off
	v_lshl_add_u64 v[192:193], s[74:75], 0, v[220:221]
	s_add_i32 m0, s25, 0x2000
	s_nop 0
	global_load_lds_dwordx4 v[192:193], off
	v_lshl_add_u64 v[192:193], v[196:197], 0, s[64:65]
	s_mov_b32 m0, s27
	s_nop 0
	global_load_lds_dwordx4 v[192:193], off
	v_lshl_add_u64 v[192:193], v[198:199], 0, s[64:65]
	s_mov_b32 m0, s42
	s_nop 0
	global_load_lds_dwordx4 v[192:193], off
	s_waitcnt vmcnt(8)
	s_waitcnt lgkmcnt(0)
	s_setprio 1
	s_barrier
	v_mfma_f32_16x16x32_bf16 v[60:63], v[76:79], v[152:155], v[60:63]
	v_mfma_f32_16x16x32_bf16 v[56:59], v[84:87], v[152:155], v[56:59]
	v_mfma_f32_16x16x32_bf16 v[52:55], v[76:79], v[168:171], v[52:55]
	v_mfma_f32_16x16x32_bf16 v[48:51], v[84:87], v[168:171], v[48:51]
	v_mfma_f32_16x16x32_bf16 v[44:47], v[76:79], v[176:179], v[44:47]
	v_mfma_f32_16x16x32_bf16 v[40:43], v[84:87], v[176:179], v[40:43]
	v_mfma_f32_16x16x32_bf16 v[36:39], v[76:79], v[184:187], v[36:39]
	v_mfma_f32_16x16x32_bf16 v[32:35], v[84:87], v[184:187], v[32:35]
	v_mfma_f32_16x16x32_bf16 v[60:63], v[80:83], v[160:163], v[60:63]
	v_mfma_f32_16x16x32_bf16 v[56:59], v[92:95], v[160:163], v[56:59]
	v_mfma_f32_16x16x32_bf16 v[52:55], v[80:83], v[172:175], v[52:55]
	v_mfma_f32_16x16x32_bf16 v[48:51], v[92:95], v[172:175], v[48:51]
	v_mfma_f32_16x16x32_bf16 v[44:47], v[80:83], v[180:183], v[44:47]
	v_mfma_f32_16x16x32_bf16 v[40:43], v[92:95], v[180:183], v[40:43]
	v_mfma_f32_16x16x32_bf16 v[36:39], v[80:83], v[188:191], v[36:39]
	v_mfma_f32_16x16x32_bf16 v[32:35], v[92:95], v[188:191], v[32:35]
	s_setprio 0
	s_setprio 1
	v_mfma_f32_16x16x32_bf16 v[28:31], v[112:115], v[152:155], v[28:31]
	v_mfma_f32_16x16x32_bf16 v[24:27], v[120:123], v[152:155], v[24:27]
	v_mfma_f32_16x16x32_bf16 v[20:23], v[112:115], v[168:171], v[20:23]
	v_mfma_f32_16x16x32_bf16 v[16:19], v[120:123], v[168:171], v[16:19]
	v_mfma_f32_16x16x32_bf16 v[12:15], v[112:115], v[176:179], v[12:15]
	v_mfma_f32_16x16x32_bf16 v[8:11], v[120:123], v[176:179], v[8:11]
	v_mfma_f32_16x16x32_bf16 v[4:7], v[112:115], v[184:187], v[4:7]
	v_mfma_f32_16x16x32_bf16 v[0:3], v[120:123], v[184:187], v[0:3]
	v_mfma_f32_16x16x32_bf16 v[28:31], v[116:119], v[160:163], v[28:31]
	v_mfma_f32_16x16x32_bf16 v[24:27], v[124:127], v[160:163], v[24:27]
	v_mfma_f32_16x16x32_bf16 v[20:23], v[116:119], v[172:175], v[20:23]
	v_mfma_f32_16x16x32_bf16 v[16:19], v[124:127], v[172:175], v[16:19]
	v_mfma_f32_16x16x32_bf16 v[12:15], v[116:119], v[180:183], v[12:15]
	v_mfma_f32_16x16x32_bf16 v[8:11], v[124:127], v[180:183], v[8:11]
	v_mfma_f32_16x16x32_bf16 v[4:7], v[116:119], v[188:191], v[4:7]
	v_mfma_f32_16x16x32_bf16 v[0:3], v[124:127], v[188:191], v[0:3]
	s_barrier
	s_setprio 0
	s_add_i32 s24, s24, 2
	s_add_u32 s7, s7, 0x100
	s_addc_u32 s23, s23, 0
	s_cmpk_gt_u32 s24, 0x55
	s_mov_b64 s[74:75], s[4:5]
	s_cbranch_scc0 .LBB0_1249
	v_readlane_b32 s4, v254, 60
	v_readlane_b32 s5, v254, 61
	s_and_b64 vcc, exec, s[4:5]
	s_cbranch_vccz .LBB0_1252
	s_barrier

.LBB0_1365:
	s_ashr_i32 s55, s54, 31
	s_lshl_b64 s[42:43], s[54:55], 20
	s_add_u32 s50, s82, s42
	s_addc_u32 s51, s83, s43
	s_and_b64 s[42:43], s[2:3], exec
	s_cselect_b32 s5, s51, s73
	s_cselect_b32 s42, s50, s72
	s_ashr_i32 s67, s66, 31
	s_lshl_b64 s[60:61], s[66:67], 20
	s_add_u32 s60, s33, s60
	s_addc_u32 s61, s53, s61
	s_and_b64 s[78:79], s[2:3], exec
	s_cselect_b32 s43, s61, s75
	s_cselect_b32 s55, s60, s74
	s_add_u32 s72, s72, 0x80080
	s_addc_u32 s73, s73, 0
	s_add_u32 s67, s74, 0x100
	s_addc_u32 s69, s75, 0
	s_mov_b32 s84, -2
	s_add_u32 s74, s72, 0xfff80080
	s_addc_u32 s75, s73, -1
	s_add_i32 vcc_lo, 0, 0x10000
	s_cmp_eq_u32 s84, 28
	s_cselect_b32 s79, s5, s75
	s_cselect_b32 s78, s42, s74
	s_cselect_b32 s75, s43, s69
	s_cselect_b32 s74, s55, s67
	s_add_i32 s8, 0, 0x14000
	v_add_u32_e32 v116, vcc_lo, v203
	v_add_u32_e32 v136, s8, v203
	ds_read_b128 v[104:107], v116
	ds_read_b128 v[108:111], v116 offset:1024
	ds_read_b128 v[112:115], v116 offset:2048
	ds_read_b128 v[116:119], v116 offset:3072
	ds_read_b128 v[124:127], v136
	ds_read_b128 v[128:131], v136 offset:1024
	ds_read_b128 v[132:135], v136 offset:2048
	ds_read_b128 v[136:139], v136 offset:3072
	v_lshl_add_u64 v[206:207], s[72:73], 0, v[214:215]
	s_add_i32 m0, s85, 0xc000
	ds_read_b128 v[160:163], v204
	ds_read_b128 v[164:167], v204 offset:1024
	ds_read_b128 v[168:171], v204 offset:2048
	ds_read_b128 v[172:175], v204 offset:3072
	ds_read_b128 v[176:179], v204 offset:4096
	ds_read_b128 v[180:183], v204 offset:5120
	ds_read_b128 v[184:187], v204 offset:6144
	ds_read_b128 v[188:191], v204 offset:7168
	global_load_lds_dwordx4 v[206:207], off
	v_lshl_add_u64 v[206:207], s[72:73], 0, v[216:217]
	s_add_i32 m0, s85, 0xe000
	s_nop 0
	global_load_lds_dwordx4 v[206:207], off
	v_mov_b32_e32 v0, v202
	v_mov_b32_e32 v1, v202
	v_mov_b32_e32 v2, v202
	v_mov_b32_e32 v3, v202
	v_mov_b32_e32 v4, v202
	v_mov_b32_e32 v5, v202
	v_mov_b32_e32 v6, v202
	v_mov_b32_e32 v7, v202
	v_mov_b32_e32 v8, v202
	v_mov_b32_e32 v9, v202
	v_mov_b32_e32 v10, v202
	v_mov_b32_e32 v11, v202
	v_mov_b32_e32 v12, v202
	v_mov_b32_e32 v13, v202
	v_mov_b32_e32 v14, v202
	v_mov_b32_e32 v15, v202
	v_mov_b32_e32 v16, v202
	v_mov_b32_e32 v17, v202
	v_mov_b32_e32 v18, v202
	v_mov_b32_e32 v19, v202
	v_mov_b32_e32 v20, v202
	v_mov_b32_e32 v21, v202
	v_mov_b32_e32 v22, v202
	v_mov_b32_e32 v23, v202
	v_mov_b32_e32 v24, v202
	v_mov_b32_e32 v25, v202
	v_mov_b32_e32 v26, v202
	v_mov_b32_e32 v27, v202
	v_mov_b32_e32 v28, v202
	v_mov_b32_e32 v29, v202
	v_mov_b32_e32 v30, v202
	v_mov_b32_e32 v31, v202
	v_mov_b32_e32 v64, v202
	v_mov_b32_e32 v65, v202
	v_mov_b32_e32 v66, v202
	v_mov_b32_e32 v67, v202
	v_mov_b32_e32 v68, v202
	v_mov_b32_e32 v69, v202
	v_mov_b32_e32 v70, v202
	v_mov_b32_e32 v71, v202
	v_mov_b32_e32 v72, v202
	v_mov_b32_e32 v73, v202
	v_mov_b32_e32 v74, v202
	v_mov_b32_e32 v75, v202
	v_mov_b32_e32 v76, v202
	v_mov_b32_e32 v77, v202
	v_mov_b32_e32 v78, v202
	v_mov_b32_e32 v79, v202
	v_mov_b32_e32 v80, v202
	v_mov_b32_e32 v81, v202
	v_mov_b32_e32 v82, v202
	v_mov_b32_e32 v83, v202
	v_mov_b32_e32 v84, v202
	v_mov_b32_e32 v85, v202
	v_mov_b32_e32 v86, v202
	v_mov_b32_e32 v87, v202
	v_mov_b32_e32 v88, v202
	v_mov_b32_e32 v89, v202
	v_mov_b32_e32 v90, v202
	v_mov_b32_e32 v91, v202
	v_mov_b32_e32 v92, v202
	v_mov_b32_e32 v93, v202
	v_mov_b32_e32 v94, v202
	v_mov_b32_e32 v95, v202
	v_mov_b32_e32 v32, v202
	v_mov_b32_e32 v33, v202
	v_mov_b32_e32 v34, v202
	v_mov_b32_e32 v35, v202
	v_mov_b32_e32 v36, v202
	v_mov_b32_e32 v37, v202
	v_mov_b32_e32 v38, v202
	v_mov_b32_e32 v39, v202
	v_mov_b32_e32 v40, v202
	v_mov_b32_e32 v41, v202
	v_mov_b32_e32 v42, v202
	v_mov_b32_e32 v43, v202
	v_mov_b32_e32 v44, v202
	v_mov_b32_e32 v45, v202
	v_mov_b32_e32 v46, v202
	v_mov_b32_e32 v47, v202
	v_mov_b32_e32 v48, v202
	v_mov_b32_e32 v49, v202
	v_mov_b32_e32 v50, v202
	v_mov_b32_e32 v51, v202
	v_mov_b32_e32 v52, v202
	v_mov_b32_e32 v53, v202
	v_mov_b32_e32 v54, v202
	v_mov_b32_e32 v55, v202
	v_mov_b32_e32 v56, v202
	v_mov_b32_e32 v57, v202
	v_mov_b32_e32 v58, v202
	v_mov_b32_e32 v59, v202
	v_mov_b32_e32 v60, v202
	v_mov_b32_e32 v61, v202
	v_mov_b32_e32 v62, v202
	v_mov_b32_e32 v63, v202
	v_mov_b32_e32 v96, v202
	v_mov_b32_e32 v97, v202
	v_mov_b32_e32 v98, v202
	v_mov_b32_e32 v99, v202
	v_mov_b32_e32 v100, v202
	v_mov_b32_e32 v101, v202
	v_mov_b32_e32 v102, v202
	v_mov_b32_e32 v103, v202
	v_mov_b32_e32 v120, v202
	v_mov_b32_e32 v121, v202
	v_mov_b32_e32 v122, v202
	v_mov_b32_e32 v123, v202
	v_mov_b32_e32 v140, v202
	v_mov_b32_e32 v141, v202
	v_mov_b32_e32 v142, v202
	v_mov_b32_e32 v143, v202
	v_mov_b32_e32 v144, v202
	v_mov_b32_e32 v145, v202
	v_mov_b32_e32 v146, v202
	v_mov_b32_e32 v147, v202
	v_mov_b32_e32 v148, v202
	v_mov_b32_e32 v149, v202
	v_mov_b32_e32 v150, v202
	v_mov_b32_e32 v151, v202
	v_mov_b32_e32 v152, v202
	v_mov_b32_e32 v153, v202
	v_mov_b32_e32 v154, v202
	v_mov_b32_e32 v155, v202
	v_mov_b32_e32 v156, v202
	v_mov_b32_e32 v157, v202
	v_mov_b32_e32 v158, v202
	v_mov_b32_e32 v159, v202
	s_branch .Lz1366_mid

.Lz1366_mid:
	s_waitcnt vmcnt(8)
	s_waitcnt lgkmcnt(0)
	s_setprio 1
	s_barrier
	v_mfma_f32_16x16x32_bf16 v[156:159], v[104:107], v[160:163], v[156:159]
	v_mfma_f32_16x16x32_bf16 v[152:155], v[112:115], v[160:163], v[152:155]
	v_mfma_f32_16x16x32_bf16 v[148:151], v[104:107], v[168:171], v[148:151]
	v_mfma_f32_16x16x32_bf16 v[144:147], v[112:115], v[168:171], v[144:147]
	v_mfma_f32_16x16x32_bf16 v[140:143], v[104:107], v[176:179], v[140:143]
	v_mfma_f32_16x16x32_bf16 v[120:123], v[112:115], v[176:179], v[120:123]
	v_mfma_f32_16x16x32_bf16 v[100:103], v[104:107], v[184:187], v[100:103]
	v_mfma_f32_16x16x32_bf16 v[96:99], v[112:115], v[184:187], v[96:99]
	v_mfma_f32_16x16x32_bf16 v[156:159], v[108:111], v[164:167], v[156:159]
	v_mfma_f32_16x16x32_bf16 v[152:155], v[116:119], v[164:167], v[152:155]
	v_mfma_f32_16x16x32_bf16 v[148:151], v[108:111], v[172:175], v[148:151]
	v_mfma_f32_16x16x32_bf16 v[144:147], v[116:119], v[172:175], v[144:147]
	v_mfma_f32_16x16x32_bf16 v[140:143], v[108:111], v[180:183], v[140:143]
	v_mfma_f32_16x16x32_bf16 v[120:123], v[116:119], v[180:183], v[120:123]
	v_mfma_f32_16x16x32_bf16 v[100:103], v[108:111], v[188:191], v[100:103]
	v_mfma_f32_16x16x32_bf16 v[96:99], v[116:119], v[188:191], v[96:99]
	s_setprio 0
	s_setprio 1
	v_mfma_f32_16x16x32_bf16 v[60:63], v[124:127], v[160:163], v[60:63]
	v_mfma_f32_16x16x32_bf16 v[56:59], v[132:135], v[160:163], v[56:59]
	v_mfma_f32_16x16x32_bf16 v[52:55], v[124:127], v[168:171], v[52:55]
	v_mfma_f32_16x16x32_bf16 v[48:51], v[132:135], v[168:171], v[48:51]
	v_mfma_f32_16x16x32_bf16 v[44:47], v[124:127], v[176:179], v[44:47]
	v_mfma_f32_16x16x32_bf16 v[40:43], v[132:135], v[176:179], v[40:43]
	v_mfma_f32_16x16x32_bf16 v[36:39], v[124:127], v[184:187], v[36:39]
	v_mfma_f32_16x16x32_bf16 v[32:35], v[132:135], v[184:187], v[32:35]
	v_mfma_f32_16x16x32_bf16 v[60:63], v[128:131], v[164:167], v[60:63]
	v_mfma_f32_16x16x32_bf16 v[56:59], v[136:139], v[164:167], v[56:59]
	v_mfma_f32_16x16x32_bf16 v[52:55], v[128:131], v[172:175], v[52:55]
	v_mfma_f32_16x16x32_bf16 v[48:51], v[136:139], v[172:175], v[48:51]
	v_mfma_f32_16x16x32_bf16 v[44:47], v[128:131], v[180:183], v[44:47]
	v_mfma_f32_16x16x32_bf16 v[40:43], v[136:139], v[180:183], v[40:43]
	v_mfma_f32_16x16x32_bf16 v[36:39], v[128:131], v[188:191], v[36:39]
	v_mfma_f32_16x16x32_bf16 v[32:35], v[136:139], v[188:191], v[32:35]
	s_barrier
	s_setprio 0
	s_add_i32 s9, vcc_lo, s81
	v_lshl_add_u64 v[206:207], s[74:75], 0, v[194:195]
	s_mov_b32 m0, s9
	ds_read_b128 v[160:163], v204 offset:16384
	ds_read_b128 v[164:167], v204 offset:17408
	ds_read_b128 v[168:171], v204 offset:18432
	ds_read_b128 v[172:175], v204 offset:19456
	ds_read_b128 v[176:179], v204 offset:20480
	ds_read_b128 v[180:183], v204 offset:21504
	ds_read_b128 v[184:187], v204 offset:22528
	ds_read_b128 v[188:191], v204 offset:23552
	global_load_lds_dwordx4 v[206:207], off
	s_add_i32 m0, s9, 0x2000
	s_add_u32 vcc_lo, s74, 0x80000
	v_lshl_add_u64 v[208:209], s[74:75], 0, v[198:199]
	s_addc_u32 vcc_hi, s75, 0
	s_add_i32 s8, s8, s81
	global_load_lds_dwordx4 v[208:209], off
	v_lshl_add_u64 v[212:213], vcc, 0, v[194:195]
	s_mov_b32 m0, s8
	v_lshl_add_u64 v[218:219], s[78:79], 0, v[196:197]
	global_load_lds_dwordx4 v[212:213], off
	v_lshl_add_u64 v[212:213], vcc, 0, v[198:199]
	s_add_i32 m0, s8, 0x2000
	s_nop 0
	global_load_lds_dwordx4 v[212:213], off
	v_lshl_add_u64 v[212:213], s[78:79], 0, v[192:193]
	s_mov_b32 m0, s85
	s_nop 0
	global_load_lds_dwordx4 v[212:213], off
	s_mov_b32 m0, s38
	s_nop 0
	global_load_lds_dwordx4 v[218:219], off
	s_waitcnt vmcnt(8)
	s_waitcnt lgkmcnt(0)
	s_setprio 1
	s_barrier
	v_mfma_f32_16x16x32_bf16 v[92:95], v[104:107], v[160:163], v[92:95]
	v_mfma_f32_16x16x32_bf16 v[88:91], v[112:115], v[160:163], v[88:91]
	v_mfma_f32_16x16x32_bf16 v[84:87], v[104:107], v[168:171], v[84:87]
	v_mfma_f32_16x16x32_bf16 v[80:83], v[112:115], v[168:171], v[80:83]
	v_mfma_f32_16x16x32_bf16 v[76:79], v[104:107], v[176:179], v[76:79]
	v_mfma_f32_16x16x32_bf16 v[72:75], v[112:115], v[176:179], v[72:75]
	v_mfma_f32_16x16x32_bf16 v[68:71], v[104:107], v[184:187], v[68:71]
	v_mfma_f32_16x16x32_bf16 v[64:67], v[112:115], v[184:187], v[64:67]
	v_mfma_f32_16x16x32_bf16 v[92:95], v[108:111], v[164:167], v[92:95]
	v_mfma_f32_16x16x32_bf16 v[88:91], v[116:119], v[164:167], v[88:91]
	v_mfma_f32_16x16x32_bf16 v[84:87], v[108:111], v[172:175], v[84:87]
	v_mfma_f32_16x16x32_bf16 v[80:83], v[116:119], v[172:175], v[80:83]
	v_mfma_f32_16x16x32_bf16 v[76:79], v[108:111], v[180:183], v[76:79]
	v_mfma_f32_16x16x32_bf16 v[72:75], v[116:119], v[180:183], v[72:75]
	v_mfma_f32_16x16x32_bf16 v[68:71], v[108:111], v[188:191], v[68:71]
	v_mfma_f32_16x16x32_bf16 v[64:67], v[116:119], v[188:191], v[64:67]
	s_setprio 0
	s_setprio 1
	v_mfma_f32_16x16x32_bf16 v[28:31], v[124:127], v[160:163], v[28:31]
	v_mfma_f32_16x16x32_bf16 v[24:27], v[132:135], v[160:163], v[24:27]
	v_mfma_f32_16x16x32_bf16 v[20:23], v[124:127], v[168:171], v[20:23]
	v_mfma_f32_16x16x32_bf16 v[16:19], v[132:135], v[168:171], v[16:19]
	v_mfma_f32_16x16x32_bf16 v[12:15], v[124:127], v[176:179], v[12:15]
	v_mfma_f32_16x16x32_bf16 v[8:11], v[132:135], v[176:179], v[8:11]
	v_mfma_f32_16x16x32_bf16 v[4:7], v[124:127], v[184:187], v[4:7]
	v_mfma_f32_16x16x32_bf16 v[0:3], v[132:135], v[184:187], v[0:3]
	v_mfma_f32_16x16x32_bf16 v[28:31], v[128:131], v[164:167], v[28:31]
	v_mfma_f32_16x16x32_bf16 v[24:27], v[136:139], v[164:167], v[24:27]
	v_mfma_f32_16x16x32_bf16 v[20:23], v[128:131], v[172:175], v[20:23]
	v_mfma_f32_16x16x32_bf16 v[16:19], v[136:139], v[172:175], v[16:19]
	v_mfma_f32_16x16x32_bf16 v[12:15], v[128:131], v[180:183], v[12:15]
	v_mfma_f32_16x16x32_bf16 v[8:11], v[136:139], v[180:183], v[8:11]
	v_mfma_f32_16x16x32_bf16 v[4:7], v[128:131], v[188:191], v[4:7]
	v_mfma_f32_16x16x32_bf16 v[0:3], v[136:139], v[188:191], v[0:3]
	s_barrier
	s_setprio 0
	s_add_i32 s8, 0, 0x18000
	s_add_i32 s9, 0, 0x1c000
	v_add_u32_e32 v116, s8, v203
	v_add_u32_e32 v136, s9, v203
	ds_read_b128 v[104:107], v116
	ds_read_b128 v[108:111], v116 offset:1024
	ds_read_b128 v[112:115], v116 offset:2048
	ds_read_b128 v[116:119], v116 offset:3072
	ds_read_b128 v[124:127], v136
	ds_read_b128 v[128:131], v136 offset:1024
	ds_read_b128 v[132:135], v136 offset:2048
	ds_read_b128 v[136:139], v136 offset:3072
	s_add_u32 s78, s78, 0x80000
	s_addc_u32 s79, s79, 0
	s_mov_b32 m0, s39
	v_lshl_add_u64 v[220:221], s[78:79], 0, v[192:193]
	ds_read_b128 v[160:163], v204 offset:32768
	ds_read_b128 v[164:167], v204 offset:33792
	ds_read_b128 v[168:171], v204 offset:34816
	ds_read_b128 v[172:175], v204 offset:35840
	ds_read_b128 v[176:179], v204 offset:36864
	ds_read_b128 v[180:183], v204 offset:37888
	ds_read_b128 v[184:187], v204 offset:38912
	ds_read_b128 v[188:191], v204 offset:39936
	global_load_lds_dwordx4 v[220:221], off
	v_lshl_add_u64 v[220:221], s[78:79], 0, v[196:197]
	s_mov_b32 m0, s94
	s_nop 0
	global_load_lds_dwordx4 v[220:221], off
	s_waitcnt vmcnt(8)
	s_waitcnt lgkmcnt(0)
	s_setprio 1
	s_barrier
	v_mfma_f32_16x16x32_bf16 v[156:159], v[104:107], v[160:163], v[156:159]
	v_mfma_f32_16x16x32_bf16 v[152:155], v[112:115], v[160:163], v[152:155]
	v_mfma_f32_16x16x32_bf16 v[148:151], v[104:107], v[168:171], v[148:151]
	v_mfma_f32_16x16x32_bf16 v[144:147], v[112:115], v[168:171], v[144:147]
	v_mfma_f32_16x16x32_bf16 v[140:143], v[104:107], v[176:179], v[140:143]
	v_mfma_f32_16x16x32_bf16 v[120:123], v[112:115], v[176:179], v[120:123]
	v_mfma_f32_16x16x32_bf16 v[100:103], v[104:107], v[184:187], v[100:103]
	v_mfma_f32_16x16x32_bf16 v[96:99], v[112:115], v[184:187], v[96:99]
	v_mfma_f32_16x16x32_bf16 v[156:159], v[108:111], v[164:167], v[156:159]
	v_mfma_f32_16x16x32_bf16 v[152:155], v[116:119], v[164:167], v[152:155]
	v_mfma_f32_16x16x32_bf16 v[148:151], v[108:111], v[172:175], v[148:151]
	v_mfma_f32_16x16x32_bf16 v[144:147], v[116:119], v[172:175], v[144:147]
	v_mfma_f32_16x16x32_bf16 v[140:143], v[108:111], v[180:183], v[140:143]
	v_mfma_f32_16x16x32_bf16 v[120:123], v[116:119], v[180:183], v[120:123]
	v_mfma_f32_16x16x32_bf16 v[100:103], v[108:111], v[188:191], v[100:103]
	v_mfma_f32_16x16x32_bf16 v[96:99], v[116:119], v[188:191], v[96:99]
	s_setprio 0
	s_setprio 1
	v_mfma_f32_16x16x32_bf16 v[60:63], v[124:127], v[160:163], v[60:63]
	v_mfma_f32_16x16x32_bf16 v[56:59], v[132:135], v[160:163], v[56:59]
	v_mfma_f32_16x16x32_bf16 v[52:55], v[124:127], v[168:171], v[52:55]
	v_mfma_f32_16x16x32_bf16 v[48:51], v[132:135], v[168:171], v[48:51]
	v_mfma_f32_16x16x32_bf16 v[44:47], v[124:127], v[176:179], v[44:47]
	v_mfma_f32_16x16x32_bf16 v[40:43], v[132:135], v[176:179], v[40:43]
	v_mfma_f32_16x16x32_bf16 v[36:39], v[124:127], v[184:187], v[36:39]
	v_mfma_f32_16x16x32_bf16 v[32:35], v[132:135], v[184:187], v[32:35]
	v_mfma_f32_16x16x32_bf16 v[60:63], v[128:131], v[164:167], v[60:63]
	v_mfma_f32_16x16x32_bf16 v[56:59], v[136:139], v[164:167], v[56:59]
	v_mfma_f32_16x16x32_bf16 v[52:55], v[128:131], v[172:175], v[52:55]
	v_mfma_f32_16x16x32_bf16 v[48:51], v[136:139], v[172:175], v[48:51]
	v_mfma_f32_16x16x32_bf16 v[44:47], v[128:131], v[180:183], v[44:47]
	v_mfma_f32_16x16x32_bf16 v[40:43], v[136:139], v[180:183], v[40:43]
	v_mfma_f32_16x16x32_bf16 v[36:39], v[128:131], v[188:191], v[36:39]
	v_mfma_f32_16x16x32_bf16 v[32:35], v[136:139], v[188:191], v[32:35]
	s_barrier
	s_setprio 0
	s_add_i32 s8, s8, s81
	v_lshl_add_u64 v[206:207], v[206:207], 0, s[64:65]
	s_mov_b32 m0, s8
	ds_read_b128 v[160:163], v204 offset:49152
	ds_read_b128 v[164:167], v204 offset:50176
	ds_read_b128 v[168:171], v204 offset:51200
	ds_read_b128 v[172:175], v204 offset:52224
	ds_read_b128 v[176:179], v204 offset:53248
	ds_read_b128 v[180:183], v204 offset:54272
	ds_read_b128 v[184:187], v204 offset:55296
	ds_read_b128 v[188:191], v204 offset:56320
	global_load_lds_dwordx4 v[206:207], off
	s_add_i32 m0, s8, 0x2000
	s_add_u32 s74, s74, 0x80080
	v_lshl_add_u64 v[206:207], v[208:209], 0, s[64:65]
	s_addc_u32 s75, s75, 0
	s_add_i32 s8, s9, s81
	global_load_lds_dwordx4 v[206:207], off
	v_lshl_add_u64 v[206:207], s[74:75], 0, v[194:195]
	s_mov_b32 m0, s8
	s_nop 0
	global_load_lds_dwordx4 v[206:207], off
	v_lshl_add_u64 v[206:207], s[74:75], 0, v[198:199]
	s_add_i32 m0, s8, 0x2000
	s_nop 0
	global_load_lds_dwordx4 v[206:207], off
	v_lshl_add_u64 v[206:207], v[212:213], 0, s[64:65]
	s_mov_b32 m0, s12
	s_nop 0
	global_load_lds_dwordx4 v[206:207], off
	v_lshl_add_u64 v[206:207], v[218:219], 0, s[64:65]
	s_mov_b32 m0, s13
	s_nop 0
	global_load_lds_dwordx4 v[206:207], off
	s_waitcnt vmcnt(8)
	s_waitcnt lgkmcnt(0)
	s_setprio 1
	s_barrier
	v_mfma_f32_16x16x32_bf16 v[92:95], v[104:107], v[160:163], v[92:95]
	v_mfma_f32_16x16x32_bf16 v[88:91], v[112:115], v[160:163], v[88:91]
	v_mfma_f32_16x16x32_bf16 v[84:87], v[104:107], v[168:171], v[84:87]
	v_mfma_f32_16x16x32_bf16 v[80:83], v[112:115], v[168:171], v[80:83]
	v_mfma_f32_16x16x32_bf16 v[76:79], v[104:107], v[176:179], v[76:79]
	v_mfma_f32_16x16x32_bf16 v[72:75], v[112:115], v[176:179], v[72:75]
	v_mfma_f32_16x16x32_bf16 v[68:71], v[104:107], v[184:187], v[68:71]
	v_mfma_f32_16x16x32_bf16 v[64:67], v[112:115], v[184:187], v[64:67]
	v_mfma_f32_16x16x32_bf16 v[92:95], v[108:111], v[164:167], v[92:95]
	v_mfma_f32_16x16x32_bf16 v[88:91], v[116:119], v[164:167], v[88:91]
	v_mfma_f32_16x16x32_bf16 v[84:87], v[108:111], v[172:175], v[84:87]
	v_mfma_f32_16x16x32_bf16 v[80:83], v[116:119], v[172:175], v[80:83]
	v_mfma_f32_16x16x32_bf16 v[76:79], v[108:111], v[180:183], v[76:79]
	v_mfma_f32_16x16x32_bf16 v[72:75], v[116:119], v[180:183], v[72:75]
	v_mfma_f32_16x16x32_bf16 v[68:71], v[108:111], v[188:191], v[68:71]
	v_mfma_f32_16x16x32_bf16 v[64:67], v[116:119], v[188:191], v[64:67]
	s_setprio 0
	s_setprio 1
	v_mfma_f32_16x16x32_bf16 v[28:31], v[124:127], v[160:163], v[28:31]
	v_mfma_f32_16x16x32_bf16 v[24:27], v[132:135], v[160:163], v[24:27]
	v_mfma_f32_16x16x32_bf16 v[20:23], v[124:127], v[168:171], v[20:23]
	v_mfma_f32_16x16x32_bf16 v[16:19], v[132:135], v[168:171], v[16:19]
	v_mfma_f32_16x16x32_bf16 v[12:15], v[124:127], v[176:179], v[12:15]
	v_mfma_f32_16x16x32_bf16 v[8:11], v[132:135], v[176:179], v[8:11]
	v_mfma_f32_16x16x32_bf16 v[4:7], v[124:127], v[184:187], v[4:7]
	v_mfma_f32_16x16x32_bf16 v[0:3], v[132:135], v[184:187], v[0:3]
	v_mfma_f32_16x16x32_bf16 v[28:31], v[128:131], v[164:167], v[28:31]
	v_mfma_f32_16x16x32_bf16 v[24:27], v[136:139], v[164:167], v[24:27]
	v_mfma_f32_16x16x32_bf16 v[20:23], v[128:131], v[172:175], v[20:23]
	v_mfma_f32_16x16x32_bf16 v[16:19], v[136:139], v[172:175], v[16:19]
	v_mfma_f32_16x16x32_bf16 v[12:15], v[128:131], v[180:183], v[12:15]
	v_mfma_f32_16x16x32_bf16 v[8:11], v[136:139], v[180:183], v[8:11]
	v_mfma_f32_16x16x32_bf16 v[4:7], v[128:131], v[188:191], v[4:7]
	v_mfma_f32_16x16x32_bf16 v[0:3], v[136:139], v[188:191], v[0:3]
	s_barrier
	s_setprio 0
	s_add_i32 s84, s84, 2
	s_add_u32 s72, s72, 0x100
	s_addc_u32 s73, s73, 0
	s_add_u32 s67, s67, 0x100
	s_addc_u32 s69, s69, 0
	s_cmp_gt_u32 s84, 29
	s_cbranch_scc0 .LBB0_1366
	s_and_b64 vcc, exec, s[30:31]
	s_cbranch_vccz .LBB0_1369
	s_barrier
